# P0's x->bf16 copy dropped; a hand-written layer-0 norm reads the f32 input directly, writes the bf16 residual copy (same rounding) and H; P0 keeps only its 63 MB of weight reads
# speedup vs baseline: 1.0028x; 1.0028x over previous
; #define LAS __attribute__((address_space(3)))
; __device__ __forceinline__ void p0_phase(const Args& a, LAS unsigned char* lds, int tid, int lane, int wave, int bid, int G) {
;     ...
;     {
;         unsigned* head = (unsigned*)(a.ws + WS_BAR) + QUEUE_WORD + 192;
;         volatile LAS unsigned* slot = (volatile LAS unsigned*)(lds + 131072 + 128);
;         bf16_t* XB0 = (bf16_t*)(a.ws + WS_XB0);
;         for (;;) {
;             if (threadIdx.x == 0) slot[0] = __hip_atomic_fetch_add(head, 1u, __ATOMIC_RELAXED, __HIP_MEMORY_SCOPE_AGENT);
;             __syncthreads();
;             const int q = (int)slot[0];
;             __syncthreads();
;             if (q >= M / 64) break;
.LBB0_123:
	s_cmp_eq_u32 s42, 0x100
	s_cbranch_scc1 .LBB0_135
	s_add_u32 s4, s78, 0x1703b00
	s_addc_u32 s5, s79, 0
	s_add_u32 s6, s78, 0xcc00000
	s_addc_u32 s7, s79, 0
	s_add_i32 s30, 0, 0x20080
	s_lshl_b32 s3, s3, 3
	s_mov_b32 s9, 0
	v_mov_b32_e32 v113, 0
	v_mov_b32_e32 v115, s30
	s_movk_i32 s31, 0x10f
	s_branch .LBB0_126

; __device__ __forceinline__ void p_norm(const Args& a, int l, int lane, int wave, int bid, int G) {
;     const int gw = bid * 8 + wave, NGW = G * 8;
;     const float* mod = (const float*)(a.ws + WS_MOD) + (size_t)l * NMOD * 3072;
;     const float* g = a.in[9] + (size_t)l * D;
;     bf16_t* H = (bf16_t*)(a.ws + WS_H);
;     const bf16_t* X = (const bf16_t*)(a.ws + (l == 0 ? WS_XB0 : WS_XB));
;     ...
;     for (int n = 0; n < NPB; ++n) {
;         const float* mp = mod + (size_t)n * 3072;
;         f32x4 gs[4], sh[4];
; #pragma unroll
;         for (int j = 0; j < 4; ++j) { gs[j] = *((const f32x4*)g + 64 * j + lane) * (*((const f32x4*)(mp + D) + 64 * j + lane) + 1.0f); sh[j] = *((const f32x4*)mp + 64 * j + lane); }
.LBB0_191:
	s_xor_b64 s[0:1], s[4:5], -1
	v_writelane_b32 v255, s0, 8
	v_mov_b32_e32 v0, v208
	s_mul_i32 s2, s66, 0x18c000
	v_writelane_b32 v255, s1, 9
	v_readfirstlane_b32 s0, v0
	s_ashr_i32 s0, s0, 6
	v_readlane_b32 s1, v254, 6
	s_add_i32 s0, s0, s1
	v_readlane_b32 s1, v253, 36
	v_readlane_b32 s8, v253, 20
	s_mov_b32 s67, s87
	v_writelane_b32 v255, s2, 10
	s_add_u32 s2, s1, s2
	v_readlane_b32 s1, v253, 37
	v_readlane_b32 s10, v253, 22
	v_readlane_b32 s11, v253, 23
	s_addc_u32 s3, s1, 0
	s_mov_b64 s[28:29], s[4:5]
	s_lshl_b64 s[4:5], s[66:67], 12
	s_mov_b64 s[6:7], s[10:11]
	s_add_u32 s6, s6, s4
	s_addc_u32 s7, s7, s5
	v_writelane_b32 v255, s28, 11
	s_and_b64 s[4:5], s[28:29], exec
	s_mov_b32 s1, 0xcc00000
	s_cselect_b32 s4, s1, 0xaa00000
	v_and_b32_e32 v50, 63, v0
	v_readlane_b32 s9, v253, 21
	s_add_u32 s8, s78, s4
	v_readlane_b32 s12, v253, 24
	v_readlane_b32 s13, v253, 25
	v_readlane_b32 s14, v253, 26
	v_readlane_b32 s15, v253, 27
	v_readlane_b32 s16, v253, 28
	v_readlane_b32 s17, v253, 29
	s_addc_u32 s9, s79, 0
	v_lshlrev_b32_e32 v172, 4, v50
	v_readlane_b32 s18, v253, 30
	v_readlane_b32 s19, v253, 31
	v_readlane_b32 s20, v253, 32
	v_readlane_b32 s21, v253, 33
	s_mov_b64 s[12:13], s[16:17]
	v_lshl_add_u64 v[48:49], s[6:7], 0, v[172:173]
	s_cmpk_lt_i32 s0, 0x1000
	v_lshlrev_b32_e32 v172, 3, v50
	s_movk_i32 s24, 0x1000
	s_mov_b64 s[14:15], s[18:19]
	s_mov_b64 s[16:17], s[20:21]
	v_writelane_b32 v255, s29, 12
	s_mov_b32 s5, s87
	v_lshl_add_u64 v[52:53], s[46:47], 0, v[172:173]
	v_lshl_add_u64 v[54:55], s[8:9], 0, v[172:173]
	s_cselect_b64 s[6:7], -1, 0
	v_lshlrev_b32_e32 v172, 4, v50
	s_mov_b32 s1, s43
	s_mov_b32 s18, s44
	s_mov_b32 s19, s87
	s_mov_b32 s20, s87
	v_readlane_b32 s22, v253, 34
	v_readlane_b32 s23, v253, 35
	s_cmp_lg_u32 s42, 0x100
	s_cbranch_scc1 .LBB0_193
	s_cmp_lg_u32 s66, 0
	s_cbranch_scc1 .LBB0_193
	v_lshlrev_b32_e32 v231, 3, v50
	s_lshl_b32 s1, s0, 11
	s_add_u32 s8, s8, s1
	s_addc_u32 s9, s9, 0
	s_add_u32 s10, s46, s1
	s_addc_u32 s11, s47, 0
	v_readlane_b32 s38, v253, 4
	v_readlane_b32 s39, v253, 5
	v_readlane_b32 s52, v253, 6
	v_readlane_b32 s53, v253, 7
	s_lshl_b32 s21, s0, 12
	s_add_u32 s38, s38, s21
	s_addc_u32 s39, s39, 0
	s_add_u32 s52, s52, s21
	s_addc_u32 s53, s53, 0
	s_cmp_lt_u32 s0, 0x400
	s_cbranch_scc0 .Lnorm0_b
.Lnorm0_a:
	global_load_dwordx4 v[236:239], v[48:49], off offset:0
	global_load_dwordx4 v[240:243], v[48:49], off offset:1024
	global_load_dwordx4 v[244:247], v[48:49], off offset:2048
	global_load_dwordx4 v[248:251], v[48:49], off offset:3072
	s_add_u32 s30, s2, 0
	s_addc_u32 s31, s3, 0
	s_add_u32 s34, s30, 0x1000
	s_addc_u32 s35, s31, 0
	global_load_dwordx4 v[32:35], v172, s[34:35] offset:0
	global_load_dwordx4 v[36:39], v172, s[34:35] offset:1024
	global_load_dwordx4 v[40:43], v172, s[34:35] offset:2048
	global_load_dwordx4 v[44:47], v172, s[34:35] offset:3072
	global_load_dwordx4 v[56:59], v172, s[30:31] offset:0
	global_load_dwordx4 v[60:63], v172, s[30:31] offset:1024
	global_load_dwordx4 v[64:67], v172, s[30:31] offset:2048
	global_load_dwordx4 v[68:71], v172, s[30:31] offset:3072
	s_add_u32 s22, s38, 0
	s_addc_u32 s23, s39, 0
	global_load_dwordx4 v[104:107], v172, s[22:23] offset:0 nt
	global_load_dwordx4 v[108:111], v172, s[22:23] offset:1024 nt
	global_load_dwordx4 v[112:115], v172, s[22:23] offset:2048 nt
	global_load_dwordx4 v[116:119], v172, s[22:23] offset:3072 nt
	s_add_u32 s22, s38, 8388608
	s_addc_u32 s23, s39, 0
	global_load_dwordx4 v[132:135], v172, s[22:23] offset:0 nt
	global_load_dwordx4 v[136:139], v172, s[22:23] offset:1024 nt
	global_load_dwordx4 v[140:143], v172, s[22:23] offset:2048 nt
	global_load_dwordx4 v[144:147], v172, s[22:23] offset:3072 nt
	s_add_u32 s22, s38, 16777216
	s_addc_u32 s23, s39, 0
	global_load_dwordx4 v[120:123], v172, s[22:23] offset:0 nt
	global_load_dwordx4 v[124:127], v172, s[22:23] offset:1024 nt
	global_load_dwordx4 v[148:151], v172, s[22:23] offset:2048 nt
	global_load_dwordx4 v[152:155], v172, s[22:23] offset:3072 nt
	s_waitcnt vmcnt(12)
	v_pk_add_f32 v[32:33], v[32:33], 1.0 op_sel_hi:[1,0]
	v_pk_add_f32 v[34:35], v[34:35], 1.0 op_sel_hi:[1,0]
	v_pk_add_f32 v[36:37], v[36:37], 1.0 op_sel_hi:[1,0]
	v_pk_add_f32 v[38:39], v[38:39], 1.0 op_sel_hi:[1,0]
	v_pk_add_f32 v[40:41], v[40:41], 1.0 op_sel_hi:[1,0]
	v_pk_add_f32 v[42:43], v[42:43], 1.0 op_sel_hi:[1,0]
	v_pk_add_f32 v[44:45], v[44:45], 1.0 op_sel_hi:[1,0]
	v_pk_add_f32 v[46:47], v[46:47], 1.0 op_sel_hi:[1,0]
	v_pk_mul_f32 v[32:33], v[236:237], v[32:33]
	v_pk_mul_f32 v[34:35], v[238:239], v[34:35]
	v_pk_mul_f32 v[36:37], v[240:241], v[36:37]
	v_pk_mul_f32 v[38:39], v[242:243], v[38:39]
	v_pk_mul_f32 v[40:41], v[244:245], v[40:41]
	v_pk_mul_f32 v[42:43], v[246:247], v[42:43]
	v_pk_mul_f32 v[44:45], v[248:249], v[44:45]
	v_pk_mul_f32 v[46:47], v[250:251], v[46:47]
	s_add_u32 s30, s2, 12288
	s_addc_u32 s31, s3, 0
	s_add_u32 s34, s30, 0x1000
	s_addc_u32 s35, s31, 0
	global_load_dwordx4 v[156:159], v172, s[34:35] offset:0
	global_load_dwordx4 v[160:163], v172, s[34:35] offset:1024
	global_load_dwordx4 v[164:167], v172, s[34:35] offset:2048
	global_load_dwordx4 v[168:171], v172, s[34:35] offset:3072
	global_load_dwordx4 v[182:185], v172, s[30:31] offset:0
	global_load_dwordx4 v[186:189], v172, s[30:31] offset:1024
	global_load_dwordx4 v[190:193], v172, s[30:31] offset:2048
	global_load_dwordx4 v[194:197], v172, s[30:31] offset:3072
	s_waitcnt vmcnt(16)
; #define NORM_LOAD(V, ROW) do { const u32x2* xr_ = (const u32x2*)(X + (size_t)(ROW) * D); _Pragma("unroll") for (int j = 0; j < 4; ++j) { const u32x2 w_ = xr_[64 * j + lane]; \
;         V[j] = (f32x4){__uint_as_float(w_.x << 16), __uint_as_float(w_.x & 0xffff0000u), __uint_as_float(w_.y << 16), __uint_as_float(w_.y & 0xffff0000u)}; } } while (0)
; __device__ __forceinline__ void p_norm(const Args& a, int l, int lane, int wave, int bid, int G) {
;     ...
;         f32x4 gs[4], sh[4];
; #pragma unroll
;         for (int j = 0; j < 4; ++j) { gs[j] = *((const f32x4*)g + 64 * j + lane) * (*((const f32x4*)(mp + D) + 64 * j + lane) + 1.0f); sh[j] = *((const f32x4*)mp + 64 * j + lane); }
; #pragma unroll 1
;         for (int r0 = gw; r0 < LP; r0 += 3 * NGW) {
;             f32x4 v0[4], v1[4], v2[4];
;             const int ra = n * LP + r0, rb = ra + NGW, rc = rb + NGW;
;             const bool hb = r0 + NGW < LP, hc = r0 + 2 * NGW < LP;
;             NORM_LOAD(v0, ra); if (hb) NORM_LOAD(v1, rb); if (hc) NORM_LOAD(v2, rc);
;             NORM_FINISH(v0, ra, gs, sh); if (hb) NORM_FINISH(v1, rb, gs, sh); if (hc) NORM_FINISH(v2, rc, gs, sh);
	v_cvt_pk_bf16_f32 v104, v104, v105
	v_cvt_pk_bf16_f32 v105, v106, v107
	v_cvt_pk_bf16_f32 v108, v108, v109
	v_cvt_pk_bf16_f32 v109, v110, v111
	v_cvt_pk_bf16_f32 v112, v112, v113
	v_cvt_pk_bf16_f32 v113, v114, v115
	v_cvt_pk_bf16_f32 v116, v116, v117
	v_cvt_pk_bf16_f32 v117, v118, v119
	s_add_u32 s36, s8, 0
	s_addc_u32 s37, s9, 0
	global_store_dwordx2 v231, v[104:105], s[36:37] offset:0 sc1
	global_store_dwordx2 v231, v[108:109], s[36:37] offset:512 sc1
	global_store_dwordx2 v231, v[112:113], s[36:37] offset:1024 sc1
	global_store_dwordx2 v231, v[116:117], s[36:37] offset:1536 sc1
	v_lshlrev_b32_e32 v198, 16, v104
	v_and_b32_e32 v199, 0xffff0000, v104
	v_lshlrev_b32_e32 v200, 16, v105
	v_and_b32_e32 v201, 0xffff0000, v105
	v_lshlrev_b32_e32 v202, 16, v108
	v_and_b32_e32 v203, 0xffff0000, v108
	v_lshlrev_b32_e32 v204, 16, v109
	v_and_b32_e32 v205, 0xffff0000, v109
	v_lshlrev_b32_e32 v206, 16, v112
	v_and_b32_e32 v207, 0xffff0000, v112
	v_lshlrev_b32_e32 v72, 16, v113
	v_and_b32_e32 v73, 0xffff0000, v113
	v_lshlrev_b32_e32 v74, 16, v116
	v_and_b32_e32 v75, 0xffff0000, v116
	v_lshlrev_b32_e32 v78, 16, v117
	v_and_b32_e32 v79, 0xffff0000, v117
	v_mul_f32_e32 v228, v199, v199
	v_fma_f32 v228, v198, v198, v228
	v_mul_f32_e32 v229, v201, v201
	v_fma_f32 v229, v200, v200, v229
	v_add_f32_e32 v228, v228, v229
	v_mul_f32_e32 v229, v203, v203
	v_fma_f32 v229, v202, v202, v229
	v_mul_f32_e32 v227, v205, v205
	v_fma_f32 v227, v204, v204, v227
	v_add_f32_e32 v229, v229, v227
	v_add_f32_e32 v228, v228, v229
	v_mul_f32_e32 v229, v207, v207
	v_fma_f32 v229, v206, v206, v229
	v_mul_f32_e32 v227, v73, v73
	v_fma_f32 v227, v72, v72, v227
	v_add_f32_e32 v229, v229, v227
	v_add_f32_e32 v228, v228, v229
	v_mul_f32_e32 v229, v75, v75
	v_fma_f32 v229, v74, v74, v229
	v_mul_f32_e32 v227, v79, v79
	v_fma_f32 v227, v78, v78, v227
	v_add_f32_e32 v229, v229, v227
	v_add_f32_e32 v228, v228, v229
	s_nop 1
	v_add_f32_dpp v228, v228, v228 quad_perm:[1,0,3,2] row_mask:0xf bank_mask:0xf
	s_nop 1
	v_add_f32_dpp v228, v228, v228 quad_perm:[2,3,0,1] row_mask:0xf bank_mask:0xf
	s_nop 1
	v_add_f32_dpp v228, v228, v228 row_half_mirror row_mask:0xf bank_mask:0xf
	s_nop 1
	v_add_f32_dpp v228, v228, v228 row_mirror row_mask:0xf bank_mask:0xf
	s_nop 1
	v_add_f32_dpp v228, v228, v228 row_bcast:15 row_mask:0xa bank_mask:0xf
	s_nop 1
	v_add_f32_dpp v228, v228, v228 row_bcast:31 row_mask:0xc bank_mask:0xf
	s_nop 1
	v_readlane_b32 s4, v228, 63
	s_nop 1
	v_mov_b32_e32 v210, s4
	v_fmamk_f32 v210, v210, 0x3a800000, v209
	v_mul_f32_e32 v227, 0x4b800000, v210
	v_cmp_gt_f32_e32 vcc, s96, v210
	s_nop 1
	v_cndmask_b32_e32 v210, v210, v227, vcc
	v_rsq_f32_e32 v210, v210
	s_nop 0
	v_mul_f32_e32 v227, 0x45800000, v210
	v_cndmask_b32_e32 v210, v210, v227, vcc
	v_pk_mul_f32 v[198:199], v[210:211], v[198:199] op_sel_hi:[0,1]
	v_pk_fma_f32 v[198:199], v[32:33], v[198:199], v[56:57]
	v_pk_mul_f32 v[200:201], v[210:211], v[200:201] op_sel_hi:[0,1]
	v_pk_fma_f32 v[200:201], v[34:35], v[200:201], v[58:59]
	v_pk_mul_f32 v[202:203], v[210:211], v[202:203] op_sel_hi:[0,1]
	v_pk_fma_f32 v[202:203], v[36:37], v[202:203], v[60:61]
	v_pk_mul_f32 v[204:205], v[210:211], v[204:205] op_sel_hi:[0,1]
	v_pk_fma_f32 v[204:205], v[38:39], v[204:205], v[62:63]
	v_pk_mul_f32 v[206:207], v[210:211], v[206:207] op_sel_hi:[0,1]
	v_pk_fma_f32 v[206:207], v[40:41], v[206:207], v[64:65]
	v_pk_mul_f32 v[72:73], v[210:211], v[72:73] op_sel_hi:[0,1]
	v_pk_fma_f32 v[72:73], v[42:43], v[72:73], v[66:67]
	v_pk_mul_f32 v[74:75], v[210:211], v[74:75] op_sel_hi:[0,1]
	v_pk_fma_f32 v[74:75], v[44:45], v[74:75], v[68:69]
	v_pk_mul_f32 v[78:79], v[210:211], v[78:79] op_sel_hi:[0,1]
	v_pk_fma_f32 v[78:79], v[46:47], v[78:79], v[70:71]
	v_cvt_pk_bf16_f32 v106, v198, v199
	v_cvt_pk_bf16_f32 v107, v200, v201
	v_cvt_pk_bf16_f32 v110, v202, v203
	v_cvt_pk_bf16_f32 v111, v204, v205
	v_cvt_pk_bf16_f32 v114, v206, v207
	v_cvt_pk_bf16_f32 v115, v72, v73
	v_cvt_pk_bf16_f32 v118, v74, v75
	v_cvt_pk_bf16_f32 v119, v78, v79
	s_add_u32 s28, s10, 0
	s_addc_u32 s29, s11, 0
	global_store_dwordx2 v231, v[106:107], s[28:29] offset:0 sc1
	global_store_dwordx2 v231, v[110:111], s[28:29] offset:512 sc1
	global_store_dwordx2 v231, v[114:115], s[28:29] offset:1024 sc1
	global_store_dwordx2 v231, v[118:119], s[28:29] offset:1536 sc1
	s_add_u32 s22, s38, 25165824
	s_addc_u32 s23, s39, 0
	global_load_dwordx4 v[104:107], v172, s[22:23] offset:0 nt
	global_load_dwordx4 v[108:111], v172, s[22:23] offset:1024 nt
	global_load_dwordx4 v[112:115], v172, s[22:23] offset:2048 nt
	global_load_dwordx4 v[116:119], v172, s[22:23] offset:3072 nt
	s_waitcnt vmcnt(24)
; #define NORM_LOAD(V, ROW) do { const u32x2* xr_ = (const u32x2*)(X + (size_t)(ROW) * D); _Pragma("unroll") for (int j = 0; j < 4; ++j) { const u32x2 w_ = xr_[64 * j + lane]; \
;         V[j] = (f32x4){__uint_as_float(w_.x << 16), __uint_as_float(w_.x & 0xffff0000u), __uint_as_float(w_.y << 16), __uint_as_float(w_.y & 0xffff0000u)}; } } while (0)
; __device__ __forceinline__ void p_norm(const Args& a, int l, int lane, int wave, int bid, int G) {
;     ...
;         f32x4 gs[4], sh[4];
; #pragma unroll
;         for (int j = 0; j < 4; ++j) { gs[j] = *((const f32x4*)g + 64 * j + lane) * (*((const f32x4*)(mp + D) + 64 * j + lane) + 1.0f); sh[j] = *((const f32x4*)mp + 64 * j + lane); }
; #pragma unroll 1
;         for (int r0 = gw; r0 < LP; r0 += 3 * NGW) {
;             f32x4 v0[4], v1[4], v2[4];
;             const int ra = n * LP + r0, rb = ra + NGW, rc = rb + NGW;
;             const bool hb = r0 + NGW < LP, hc = r0 + 2 * NGW < LP;
;             NORM_LOAD(v0, ra); if (hb) NORM_LOAD(v1, rb); if (hc) NORM_LOAD(v2, rc);
;             NORM_FINISH(v0, ra, gs, sh); if (hb) NORM_FINISH(v1, rb, gs, sh); if (hc) NORM_FINISH(v2, rc, gs, sh);
	v_cvt_pk_bf16_f32 v132, v132, v133
	v_cvt_pk_bf16_f32 v133, v134, v135
	v_cvt_pk_bf16_f32 v136, v136, v137
	v_cvt_pk_bf16_f32 v137, v138, v139
	v_cvt_pk_bf16_f32 v140, v140, v141
	v_cvt_pk_bf16_f32 v141, v142, v143
	v_cvt_pk_bf16_f32 v144, v144, v145
	v_cvt_pk_bf16_f32 v145, v146, v147
	s_add_u32 s36, s8, 4194304
	s_addc_u32 s37, s9, 0
	global_store_dwordx2 v231, v[132:133], s[36:37] offset:0 sc1
	global_store_dwordx2 v231, v[136:137], s[36:37] offset:512 sc1
	global_store_dwordx2 v231, v[140:141], s[36:37] offset:1024 sc1
	global_store_dwordx2 v231, v[144:145], s[36:37] offset:1536 sc1
	v_lshlrev_b32_e32 v198, 16, v132
	v_and_b32_e32 v199, 0xffff0000, v132
	v_lshlrev_b32_e32 v200, 16, v133
	v_and_b32_e32 v201, 0xffff0000, v133
	v_lshlrev_b32_e32 v202, 16, v136
	v_and_b32_e32 v203, 0xffff0000, v136
	v_lshlrev_b32_e32 v204, 16, v137
	v_and_b32_e32 v205, 0xffff0000, v137
	v_lshlrev_b32_e32 v206, 16, v140
	v_and_b32_e32 v207, 0xffff0000, v140
	v_lshlrev_b32_e32 v72, 16, v141
	v_and_b32_e32 v73, 0xffff0000, v141
	v_lshlrev_b32_e32 v74, 16, v144
	v_and_b32_e32 v75, 0xffff0000, v144
	v_lshlrev_b32_e32 v78, 16, v145
	v_and_b32_e32 v79, 0xffff0000, v145
	v_mul_f32_e32 v228, v199, v199
	v_fma_f32 v228, v198, v198, v228
	v_mul_f32_e32 v229, v201, v201
	v_fma_f32 v229, v200, v200, v229
	v_add_f32_e32 v228, v228, v229
	v_mul_f32_e32 v229, v203, v203
	v_fma_f32 v229, v202, v202, v229
	v_mul_f32_e32 v227, v205, v205
	v_fma_f32 v227, v204, v204, v227
	v_add_f32_e32 v229, v229, v227
	v_add_f32_e32 v228, v228, v229
	v_mul_f32_e32 v229, v207, v207
	v_fma_f32 v229, v206, v206, v229
	v_mul_f32_e32 v227, v73, v73
	v_fma_f32 v227, v72, v72, v227
	v_add_f32_e32 v229, v229, v227
	v_add_f32_e32 v228, v228, v229
	v_mul_f32_e32 v229, v75, v75
	v_fma_f32 v229, v74, v74, v229
	v_mul_f32_e32 v227, v79, v79
	v_fma_f32 v227, v78, v78, v227
	v_add_f32_e32 v229, v229, v227
	v_add_f32_e32 v228, v228, v229
	s_nop 1
	v_add_f32_dpp v228, v228, v228 quad_perm:[1,0,3,2] row_mask:0xf bank_mask:0xf
	s_nop 1
	v_add_f32_dpp v228, v228, v228 quad_perm:[2,3,0,1] row_mask:0xf bank_mask:0xf
	s_nop 1
	v_add_f32_dpp v228, v228, v228 row_half_mirror row_mask:0xf bank_mask:0xf
	s_nop 1
	v_add_f32_dpp v228, v228, v228 row_mirror row_mask:0xf bank_mask:0xf
	s_nop 1
	v_add_f32_dpp v228, v228, v228 row_bcast:15 row_mask:0xa bank_mask:0xf
	s_nop 1
	v_add_f32_dpp v228, v228, v228 row_bcast:31 row_mask:0xc bank_mask:0xf
	s_nop 1
	v_readlane_b32 s4, v228, 63
	s_nop 1
	v_mov_b32_e32 v210, s4
	v_fmamk_f32 v210, v210, 0x3a800000, v209
	v_mul_f32_e32 v227, 0x4b800000, v210
	v_cmp_gt_f32_e32 vcc, s96, v210
	s_nop 1
	v_cndmask_b32_e32 v210, v210, v227, vcc
	v_rsq_f32_e32 v210, v210
	s_nop 0
	v_mul_f32_e32 v227, 0x45800000, v210
	v_cndmask_b32_e32 v210, v210, v227, vcc
	v_pk_mul_f32 v[198:199], v[210:211], v[198:199] op_sel_hi:[0,1]
	v_pk_fma_f32 v[198:199], v[32:33], v[198:199], v[56:57]
	v_pk_mul_f32 v[200:201], v[210:211], v[200:201] op_sel_hi:[0,1]
	v_pk_fma_f32 v[200:201], v[34:35], v[200:201], v[58:59]
	v_pk_mul_f32 v[202:203], v[210:211], v[202:203] op_sel_hi:[0,1]
	v_pk_fma_f32 v[202:203], v[36:37], v[202:203], v[60:61]
	v_pk_mul_f32 v[204:205], v[210:211], v[204:205] op_sel_hi:[0,1]
	v_pk_fma_f32 v[204:205], v[38:39], v[204:205], v[62:63]
	v_pk_mul_f32 v[206:207], v[210:211], v[206:207] op_sel_hi:[0,1]
	v_pk_fma_f32 v[206:207], v[40:41], v[206:207], v[64:65]
	v_pk_mul_f32 v[72:73], v[210:211], v[72:73] op_sel_hi:[0,1]
	v_pk_fma_f32 v[72:73], v[42:43], v[72:73], v[66:67]
	v_pk_mul_f32 v[74:75], v[210:211], v[74:75] op_sel_hi:[0,1]
	v_pk_fma_f32 v[74:75], v[44:45], v[74:75], v[68:69]
	v_pk_mul_f32 v[78:79], v[210:211], v[78:79] op_sel_hi:[0,1]
	v_pk_fma_f32 v[78:79], v[46:47], v[78:79], v[70:71]
	v_cvt_pk_bf16_f32 v134, v198, v199
	v_cvt_pk_bf16_f32 v135, v200, v201
	v_cvt_pk_bf16_f32 v138, v202, v203
	v_cvt_pk_bf16_f32 v139, v204, v205
	v_cvt_pk_bf16_f32 v142, v206, v207
	v_cvt_pk_bf16_f32 v143, v72, v73
	v_cvt_pk_bf16_f32 v146, v74, v75
	v_cvt_pk_bf16_f32 v147, v78, v79
	s_add_u32 s28, s10, 4194304
	s_addc_u32 s29, s11, 0
	global_store_dwordx2 v231, v[134:135], s[28:29] offset:0 sc1
	global_store_dwordx2 v231, v[138:139], s[28:29] offset:512 sc1
	global_store_dwordx2 v231, v[142:143], s[28:29] offset:1024 sc1
	global_store_dwordx2 v231, v[146:147], s[28:29] offset:1536 sc1
	s_add_u32 s22, s38, 33554432
	s_addc_u32 s23, s39, 0
	global_load_dwordx4 v[132:135], v172, s[22:23] offset:0 nt
	global_load_dwordx4 v[136:139], v172, s[22:23] offset:1024 nt
	global_load_dwordx4 v[140:143], v172, s[22:23] offset:2048 nt
	global_load_dwordx4 v[144:147], v172, s[22:23] offset:3072 nt
	s_waitcnt vmcnt(24)
	v_pk_add_f32 v[156:157], v[156:157], 1.0 op_sel_hi:[1,0]
	v_pk_add_f32 v[158:159], v[158:159], 1.0 op_sel_hi:[1,0]
	v_pk_add_f32 v[160:161], v[160:161], 1.0 op_sel_hi:[1,0]
	v_pk_add_f32 v[162:163], v[162:163], 1.0 op_sel_hi:[1,0]
	v_pk_add_f32 v[164:165], v[164:165], 1.0 op_sel_hi:[1,0]
	v_pk_add_f32 v[166:167], v[166:167], 1.0 op_sel_hi:[1,0]
	v_pk_add_f32 v[168:169], v[168:169], 1.0 op_sel_hi:[1,0]
	v_pk_add_f32 v[170:171], v[170:171], 1.0 op_sel_hi:[1,0]
	v_pk_mul_f32 v[156:157], v[236:237], v[156:157]
	v_pk_mul_f32 v[158:159], v[238:239], v[158:159]
	v_pk_mul_f32 v[160:161], v[240:241], v[160:161]
	v_pk_mul_f32 v[162:163], v[242:243], v[162:163]
	v_pk_mul_f32 v[164:165], v[244:245], v[164:165]
	v_pk_mul_f32 v[166:167], v[246:247], v[166:167]
	v_pk_mul_f32 v[168:169], v[248:249], v[168:169]
	v_pk_mul_f32 v[170:171], v[250:251], v[170:171]
	s_add_u32 s30, s2, 24576
	s_addc_u32 s31, s3, 0
	s_add_u32 s34, s30, 0x1000
	s_addc_u32 s35, s31, 0
	global_load_dwordx4 v[32:35], v172, s[34:35] offset:0
	global_load_dwordx4 v[36:39], v172, s[34:35] offset:1024
	global_load_dwordx4 v[40:43], v172, s[34:35] offset:2048
	global_load_dwordx4 v[44:47], v172, s[34:35] offset:3072
	global_load_dwordx4 v[56:59], v172, s[30:31] offset:0
	global_load_dwordx4 v[60:63], v172, s[30:31] offset:1024
	global_load_dwordx4 v[64:67], v172, s[30:31] offset:2048
	global_load_dwordx4 v[68:71], v172, s[30:31] offset:3072
	s_waitcnt vmcnt(40)
; #define NORM_LOAD(V, ROW) do { const u32x2* xr_ = (const u32x2*)(X + (size_t)(ROW) * D); _Pragma("unroll") for (int j = 0; j < 4; ++j) { const u32x2 w_ = xr_[64 * j + lane]; \
;         V[j] = (f32x4){__uint_as_float(w_.x << 16), __uint_as_float(w_.x & 0xffff0000u), __uint_as_float(w_.y << 16), __uint_as_float(w_.y & 0xffff0000u)}; } } while (0)
; __device__ __forceinline__ void p_norm(const Args& a, int l, int lane, int wave, int bid, int G) {
;     ...
;         f32x4 gs[4], sh[4];
; #pragma unroll
;         for (int j = 0; j < 4; ++j) { gs[j] = *((const f32x4*)g + 64 * j + lane) * (*((const f32x4*)(mp + D) + 64 * j + lane) + 1.0f); sh[j] = *((const f32x4*)mp + 64 * j + lane); }
; #pragma unroll 1
;         for (int r0 = gw; r0 < LP; r0 += 3 * NGW) {
;             f32x4 v0[4], v1[4], v2[4];
;             const int ra = n * LP + r0, rb = ra + NGW, rc = rb + NGW;
;             const bool hb = r0 + NGW < LP, hc = r0 + 2 * NGW < LP;
;             NORM_LOAD(v0, ra); if (hb) NORM_LOAD(v1, rb); if (hc) NORM_LOAD(v2, rc);
;             NORM_FINISH(v0, ra, gs, sh); if (hb) NORM_FINISH(v1, rb, gs, sh); if (hc) NORM_FINISH(v2, rc, gs, sh);
	v_cvt_pk_bf16_f32 v120, v120, v121
	v_cvt_pk_bf16_f32 v121, v122, v123
	v_cvt_pk_bf16_f32 v124, v124, v125
	v_cvt_pk_bf16_f32 v125, v126, v127
	v_cvt_pk_bf16_f32 v148, v148, v149
	v_cvt_pk_bf16_f32 v149, v150, v151
	v_cvt_pk_bf16_f32 v152, v152, v153
	v_cvt_pk_bf16_f32 v153, v154, v155
	s_add_u32 s36, s8, 8388608
	s_addc_u32 s37, s9, 0
	global_store_dwordx2 v231, v[120:121], s[36:37] offset:0 sc1
	global_store_dwordx2 v231, v[124:125], s[36:37] offset:512 sc1
	global_store_dwordx2 v231, v[148:149], s[36:37] offset:1024 sc1
	global_store_dwordx2 v231, v[152:153], s[36:37] offset:1536 sc1
	v_lshlrev_b32_e32 v198, 16, v120
	v_and_b32_e32 v199, 0xffff0000, v120
	v_lshlrev_b32_e32 v200, 16, v121
	v_and_b32_e32 v201, 0xffff0000, v121
	v_lshlrev_b32_e32 v202, 16, v124
	v_and_b32_e32 v203, 0xffff0000, v124
	v_lshlrev_b32_e32 v204, 16, v125
	v_and_b32_e32 v205, 0xffff0000, v125
	v_lshlrev_b32_e32 v206, 16, v148
	v_and_b32_e32 v207, 0xffff0000, v148
	v_lshlrev_b32_e32 v72, 16, v149
	v_and_b32_e32 v73, 0xffff0000, v149
	v_lshlrev_b32_e32 v74, 16, v152
	v_and_b32_e32 v75, 0xffff0000, v152
	v_lshlrev_b32_e32 v78, 16, v153
	v_and_b32_e32 v79, 0xffff0000, v153
	v_mul_f32_e32 v228, v199, v199
	v_fma_f32 v228, v198, v198, v228
	v_mul_f32_e32 v229, v201, v201
	v_fma_f32 v229, v200, v200, v229
	v_add_f32_e32 v228, v228, v229
	v_mul_f32_e32 v229, v203, v203
	v_fma_f32 v229, v202, v202, v229
	v_mul_f32_e32 v227, v205, v205
	v_fma_f32 v227, v204, v204, v227
	v_add_f32_e32 v229, v229, v227
	v_add_f32_e32 v228, v228, v229
	v_mul_f32_e32 v229, v207, v207
	v_fma_f32 v229, v206, v206, v229
	v_mul_f32_e32 v227, v73, v73
	v_fma_f32 v227, v72, v72, v227
	v_add_f32_e32 v229, v229, v227
	v_add_f32_e32 v228, v228, v229
	v_mul_f32_e32 v229, v75, v75
	v_fma_f32 v229, v74, v74, v229
	v_mul_f32_e32 v227, v79, v79
	v_fma_f32 v227, v78, v78, v227
	v_add_f32_e32 v229, v229, v227
	v_add_f32_e32 v228, v228, v229
	s_nop 1
	v_add_f32_dpp v228, v228, v228 quad_perm:[1,0,3,2] row_mask:0xf bank_mask:0xf
	s_nop 1
	v_add_f32_dpp v228, v228, v228 quad_perm:[2,3,0,1] row_mask:0xf bank_mask:0xf
	s_nop 1
	v_add_f32_dpp v228, v228, v228 row_half_mirror row_mask:0xf bank_mask:0xf
	s_nop 1
	v_add_f32_dpp v228, v228, v228 row_mirror row_mask:0xf bank_mask:0xf
	s_nop 1
	v_add_f32_dpp v228, v228, v228 row_bcast:15 row_mask:0xa bank_mask:0xf
	s_nop 1
	v_add_f32_dpp v228, v228, v228 row_bcast:31 row_mask:0xc bank_mask:0xf
	s_nop 1
	v_readlane_b32 s4, v228, 63
	s_nop 1
	v_mov_b32_e32 v210, s4
	v_fmamk_f32 v210, v210, 0x3a800000, v209
	v_mul_f32_e32 v227, 0x4b800000, v210
	v_cmp_gt_f32_e32 vcc, s96, v210
	s_nop 1
	v_cndmask_b32_e32 v210, v210, v227, vcc
	v_rsq_f32_e32 v210, v210
	s_nop 0
	v_mul_f32_e32 v227, 0x45800000, v210
	v_cndmask_b32_e32 v210, v210, v227, vcc
	v_pk_mul_f32 v[198:199], v[210:211], v[198:199] op_sel_hi:[0,1]
	v_pk_fma_f32 v[198:199], v[156:157], v[198:199], v[182:183]
	v_pk_mul_f32 v[200:201], v[210:211], v[200:201] op_sel_hi:[0,1]
	v_pk_fma_f32 v[200:201], v[158:159], v[200:201], v[184:185]
	v_pk_mul_f32 v[202:203], v[210:211], v[202:203] op_sel_hi:[0,1]
	v_pk_fma_f32 v[202:203], v[160:161], v[202:203], v[186:187]
	v_pk_mul_f32 v[204:205], v[210:211], v[204:205] op_sel_hi:[0,1]
	v_pk_fma_f32 v[204:205], v[162:163], v[204:205], v[188:189]
	v_pk_mul_f32 v[206:207], v[210:211], v[206:207] op_sel_hi:[0,1]
	v_pk_fma_f32 v[206:207], v[164:165], v[206:207], v[190:191]
	v_pk_mul_f32 v[72:73], v[210:211], v[72:73] op_sel_hi:[0,1]
	v_pk_fma_f32 v[72:73], v[166:167], v[72:73], v[192:193]
	v_pk_mul_f32 v[74:75], v[210:211], v[74:75] op_sel_hi:[0,1]
	v_pk_fma_f32 v[74:75], v[168:169], v[74:75], v[194:195]
	v_pk_mul_f32 v[78:79], v[210:211], v[78:79] op_sel_hi:[0,1]
	v_pk_fma_f32 v[78:79], v[170:171], v[78:79], v[196:197]
	v_cvt_pk_bf16_f32 v122, v198, v199
	v_cvt_pk_bf16_f32 v123, v200, v201
	v_cvt_pk_bf16_f32 v126, v202, v203
	v_cvt_pk_bf16_f32 v127, v204, v205
	v_cvt_pk_bf16_f32 v150, v206, v207
	v_cvt_pk_bf16_f32 v151, v72, v73
	v_cvt_pk_bf16_f32 v154, v74, v75
	v_cvt_pk_bf16_f32 v155, v78, v79
	s_add_u32 s28, s10, 8388608
	s_addc_u32 s29, s11, 0
	global_store_dwordx2 v231, v[122:123], s[28:29] offset:0 sc1
	global_store_dwordx2 v231, v[126:127], s[28:29] offset:512 sc1
	global_store_dwordx2 v231, v[150:151], s[28:29] offset:1024 sc1
	global_store_dwordx2 v231, v[154:155], s[28:29] offset:1536 sc1
	s_add_u32 s22, s38, 41943040
	s_addc_u32 s23, s39, 0
	global_load_dwordx4 v[120:123], v172, s[22:23] offset:0 nt
	global_load_dwordx4 v[124:127], v172, s[22:23] offset:1024 nt
	global_load_dwordx4 v[148:151], v172, s[22:23] offset:2048 nt
	global_load_dwordx4 v[152:155], v172, s[22:23] offset:3072 nt
	s_waitcnt vmcnt(32)
; #define NORM_LOAD(V, ROW) do { const u32x2* xr_ = (const u32x2*)(X + (size_t)(ROW) * D); _Pragma("unroll") for (int j = 0; j < 4; ++j) { const u32x2 w_ = xr_[64 * j + lane]; \
;         V[j] = (f32x4){__uint_as_float(w_.x << 16), __uint_as_float(w_.x & 0xffff0000u), __uint_as_float(w_.y << 16), __uint_as_float(w_.y & 0xffff0000u)}; } } while (0)
; __device__ __forceinline__ void p_norm(const Args& a, int l, int lane, int wave, int bid, int G) {
;     ...
;         f32x4 gs[4], sh[4];
; #pragma unroll
;         for (int j = 0; j < 4; ++j) { gs[j] = *((const f32x4*)g + 64 * j + lane) * (*((const f32x4*)(mp + D) + 64 * j + lane) + 1.0f); sh[j] = *((const f32x4*)mp + 64 * j + lane); }
; #pragma unroll 1
;         for (int r0 = gw; r0 < LP; r0 += 3 * NGW) {
;             f32x4 v0[4], v1[4], v2[4];
;             const int ra = n * LP + r0, rb = ra + NGW, rc = rb + NGW;
;             const bool hb = r0 + NGW < LP, hc = r0 + 2 * NGW < LP;
;             NORM_LOAD(v0, ra); if (hb) NORM_LOAD(v1, rb); if (hc) NORM_LOAD(v2, rc);
;             NORM_FINISH(v0, ra, gs, sh); if (hb) NORM_FINISH(v1, rb, gs, sh); if (hc) NORM_FINISH(v2, rc, gs, sh);
	v_cvt_pk_bf16_f32 v104, v104, v105
	v_cvt_pk_bf16_f32 v105, v106, v107
	v_cvt_pk_bf16_f32 v108, v108, v109
	v_cvt_pk_bf16_f32 v109, v110, v111
	v_cvt_pk_bf16_f32 v112, v112, v113
	v_cvt_pk_bf16_f32 v113, v114, v115
	v_cvt_pk_bf16_f32 v116, v116, v117
	v_cvt_pk_bf16_f32 v117, v118, v119
	s_add_u32 s36, s8, 12582912
	s_addc_u32 s37, s9, 0
	global_store_dwordx2 v231, v[104:105], s[36:37] offset:0 sc1
	global_store_dwordx2 v231, v[108:109], s[36:37] offset:512 sc1
	global_store_dwordx2 v231, v[112:113], s[36:37] offset:1024 sc1
	global_store_dwordx2 v231, v[116:117], s[36:37] offset:1536 sc1
	v_lshlrev_b32_e32 v198, 16, v104
	v_and_b32_e32 v199, 0xffff0000, v104
	v_lshlrev_b32_e32 v200, 16, v105
	v_and_b32_e32 v201, 0xffff0000, v105
	v_lshlrev_b32_e32 v202, 16, v108
	v_and_b32_e32 v203, 0xffff0000, v108
	v_lshlrev_b32_e32 v204, 16, v109
	v_and_b32_e32 v205, 0xffff0000, v109
	v_lshlrev_b32_e32 v206, 16, v112
	v_and_b32_e32 v207, 0xffff0000, v112
	v_lshlrev_b32_e32 v72, 16, v113
	v_and_b32_e32 v73, 0xffff0000, v113
	v_lshlrev_b32_e32 v74, 16, v116
	v_and_b32_e32 v75, 0xffff0000, v116
	v_lshlrev_b32_e32 v78, 16, v117
	v_and_b32_e32 v79, 0xffff0000, v117
	v_mul_f32_e32 v228, v199, v199
	v_fma_f32 v228, v198, v198, v228
	v_mul_f32_e32 v229, v201, v201
	v_fma_f32 v229, v200, v200, v229
	v_add_f32_e32 v228, v228, v229
	v_mul_f32_e32 v229, v203, v203
	v_fma_f32 v229, v202, v202, v229
	v_mul_f32_e32 v227, v205, v205
	v_fma_f32 v227, v204, v204, v227
	v_add_f32_e32 v229, v229, v227
	v_add_f32_e32 v228, v228, v229
	v_mul_f32_e32 v229, v207, v207
	v_fma_f32 v229, v206, v206, v229
	v_mul_f32_e32 v227, v73, v73
	v_fma_f32 v227, v72, v72, v227
	v_add_f32_e32 v229, v229, v227
	v_add_f32_e32 v228, v228, v229
	v_mul_f32_e32 v229, v75, v75
	v_fma_f32 v229, v74, v74, v229
	v_mul_f32_e32 v227, v79, v79
	v_fma_f32 v227, v78, v78, v227
	v_add_f32_e32 v229, v229, v227
	v_add_f32_e32 v228, v228, v229
	s_nop 1
	v_add_f32_dpp v228, v228, v228 quad_perm:[1,0,3,2] row_mask:0xf bank_mask:0xf
	s_nop 1
	v_add_f32_dpp v228, v228, v228 quad_perm:[2,3,0,1] row_mask:0xf bank_mask:0xf
	s_nop 1
	v_add_f32_dpp v228, v228, v228 row_half_mirror row_mask:0xf bank_mask:0xf
	s_nop 1
	v_add_f32_dpp v228, v228, v228 row_mirror row_mask:0xf bank_mask:0xf
	s_nop 1
	v_add_f32_dpp v228, v228, v228 row_bcast:15 row_mask:0xa bank_mask:0xf
	s_nop 1
	v_add_f32_dpp v228, v228, v228 row_bcast:31 row_mask:0xc bank_mask:0xf
	s_nop 1
	v_readlane_b32 s4, v228, 63
	s_nop 1
	v_mov_b32_e32 v210, s4
	v_fmamk_f32 v210, v210, 0x3a800000, v209
	v_mul_f32_e32 v227, 0x4b800000, v210
	v_cmp_gt_f32_e32 vcc, s96, v210
	s_nop 1
	v_cndmask_b32_e32 v210, v210, v227, vcc
	v_rsq_f32_e32 v210, v210
	s_nop 0
	v_mul_f32_e32 v227, 0x45800000, v210
	v_cndmask_b32_e32 v210, v210, v227, vcc
	v_pk_mul_f32 v[198:199], v[210:211], v[198:199] op_sel_hi:[0,1]
	v_pk_fma_f32 v[198:199], v[156:157], v[198:199], v[182:183]
	v_pk_mul_f32 v[200:201], v[210:211], v[200:201] op_sel_hi:[0,1]
	v_pk_fma_f32 v[200:201], v[158:159], v[200:201], v[184:185]
	v_pk_mul_f32 v[202:203], v[210:211], v[202:203] op_sel_hi:[0,1]
	v_pk_fma_f32 v[202:203], v[160:161], v[202:203], v[186:187]
	v_pk_mul_f32 v[204:205], v[210:211], v[204:205] op_sel_hi:[0,1]
	v_pk_fma_f32 v[204:205], v[162:163], v[204:205], v[188:189]
	v_pk_mul_f32 v[206:207], v[210:211], v[206:207] op_sel_hi:[0,1]
	v_pk_fma_f32 v[206:207], v[164:165], v[206:207], v[190:191]
	v_pk_mul_f32 v[72:73], v[210:211], v[72:73] op_sel_hi:[0,1]
	v_pk_fma_f32 v[72:73], v[166:167], v[72:73], v[192:193]
	v_pk_mul_f32 v[74:75], v[210:211], v[74:75] op_sel_hi:[0,1]
	v_pk_fma_f32 v[74:75], v[168:169], v[74:75], v[194:195]
	v_pk_mul_f32 v[78:79], v[210:211], v[78:79] op_sel_hi:[0,1]
	v_pk_fma_f32 v[78:79], v[170:171], v[78:79], v[196:197]
	v_cvt_pk_bf16_f32 v106, v198, v199
	v_cvt_pk_bf16_f32 v107, v200, v201
	v_cvt_pk_bf16_f32 v110, v202, v203
	v_cvt_pk_bf16_f32 v111, v204, v205
	v_cvt_pk_bf16_f32 v114, v206, v207
	v_cvt_pk_bf16_f32 v115, v72, v73
	v_cvt_pk_bf16_f32 v118, v74, v75
	v_cvt_pk_bf16_f32 v119, v78, v79
	s_add_u32 s28, s10, 12582912
	s_addc_u32 s29, s11, 0
	global_store_dwordx2 v231, v[106:107], s[28:29] offset:0 sc1
	global_store_dwordx2 v231, v[110:111], s[28:29] offset:512 sc1
	global_store_dwordx2 v231, v[114:115], s[28:29] offset:1024 sc1
	global_store_dwordx2 v231, v[118:119], s[28:29] offset:1536 sc1
	s_add_u32 s22, s38, 50331648
	s_addc_u32 s23, s39, 0
	global_load_dwordx4 v[104:107], v172, s[22:23] offset:0 nt
	global_load_dwordx4 v[108:111], v172, s[22:23] offset:1024 nt
	global_load_dwordx4 v[112:115], v172, s[22:23] offset:2048 nt
	global_load_dwordx4 v[116:119], v172, s[22:23] offset:3072 nt
	s_waitcnt vmcnt(24)
	v_pk_add_f32 v[32:33], v[32:33], 1.0 op_sel_hi:[1,0]
	v_pk_add_f32 v[34:35], v[34:35], 1.0 op_sel_hi:[1,0]
	v_pk_add_f32 v[36:37], v[36:37], 1.0 op_sel_hi:[1,0]
	v_pk_add_f32 v[38:39], v[38:39], 1.0 op_sel_hi:[1,0]
	v_pk_add_f32 v[40:41], v[40:41], 1.0 op_sel_hi:[1,0]
	v_pk_add_f32 v[42:43], v[42:43], 1.0 op_sel_hi:[1,0]
	v_pk_add_f32 v[44:45], v[44:45], 1.0 op_sel_hi:[1,0]
	v_pk_add_f32 v[46:47], v[46:47], 1.0 op_sel_hi:[1,0]
	v_pk_mul_f32 v[32:33], v[236:237], v[32:33]
	v_pk_mul_f32 v[34:35], v[238:239], v[34:35]
	v_pk_mul_f32 v[36:37], v[240:241], v[36:37]
	v_pk_mul_f32 v[38:39], v[242:243], v[38:39]
	v_pk_mul_f32 v[40:41], v[244:245], v[40:41]
	v_pk_mul_f32 v[42:43], v[246:247], v[42:43]
	v_pk_mul_f32 v[44:45], v[248:249], v[44:45]
	v_pk_mul_f32 v[46:47], v[250:251], v[46:47]
	s_add_u32 s30, s2, 36864
	s_addc_u32 s31, s3, 0
	s_add_u32 s34, s30, 0x1000
	s_addc_u32 s35, s31, 0
	global_load_dwordx4 v[156:159], v172, s[34:35] offset:0
	global_load_dwordx4 v[160:163], v172, s[34:35] offset:1024
	global_load_dwordx4 v[164:167], v172, s[34:35] offset:2048
	global_load_dwordx4 v[168:171], v172, s[34:35] offset:3072
	global_load_dwordx4 v[182:185], v172, s[30:31] offset:0
	global_load_dwordx4 v[186:189], v172, s[30:31] offset:1024
	global_load_dwordx4 v[190:193], v172, s[30:31] offset:2048
	global_load_dwordx4 v[194:197], v172, s[30:31] offset:3072
	s_waitcnt vmcnt(40)
; #define NORM_LOAD(V, ROW) do { const u32x2* xr_ = (const u32x2*)(X + (size_t)(ROW) * D); _Pragma("unroll") for (int j = 0; j < 4; ++j) { const u32x2 w_ = xr_[64 * j + lane]; \
;         V[j] = (f32x4){__uint_as_float(w_.x << 16), __uint_as_float(w_.x & 0xffff0000u), __uint_as_float(w_.y << 16), __uint_as_float(w_.y & 0xffff0000u)}; } } while (0)
; __device__ __forceinline__ void p_norm(const Args& a, int l, int lane, int wave, int bid, int G) {
;     ...
;         f32x4 gs[4], sh[4];
; #pragma unroll
;         for (int j = 0; j < 4; ++j) { gs[j] = *((const f32x4*)g + 64 * j + lane) * (*((const f32x4*)(mp + D) + 64 * j + lane) + 1.0f); sh[j] = *((const f32x4*)mp + 64 * j + lane); }
; #pragma unroll 1
;         for (int r0 = gw; r0 < LP; r0 += 3 * NGW) {
;             f32x4 v0[4], v1[4], v2[4];
;             const int ra = n * LP + r0, rb = ra + NGW, rc = rb + NGW;
;             const bool hb = r0 + NGW < LP, hc = r0 + 2 * NGW < LP;
;             NORM_LOAD(v0, ra); if (hb) NORM_LOAD(v1, rb); if (hc) NORM_LOAD(v2, rc);
;             NORM_FINISH(v0, ra, gs, sh); if (hb) NORM_FINISH(v1, rb, gs, sh); if (hc) NORM_FINISH(v2, rc, gs, sh);
	v_cvt_pk_bf16_f32 v132, v132, v133
	v_cvt_pk_bf16_f32 v133, v134, v135
	v_cvt_pk_bf16_f32 v136, v136, v137
	v_cvt_pk_bf16_f32 v137, v138, v139
	v_cvt_pk_bf16_f32 v140, v140, v141
	v_cvt_pk_bf16_f32 v141, v142, v143
	v_cvt_pk_bf16_f32 v144, v144, v145
	v_cvt_pk_bf16_f32 v145, v146, v147
	s_add_u32 s36, s8, 16777216
	s_addc_u32 s37, s9, 0
	global_store_dwordx2 v231, v[132:133], s[36:37] offset:0 sc1
	global_store_dwordx2 v231, v[136:137], s[36:37] offset:512 sc1
	global_store_dwordx2 v231, v[140:141], s[36:37] offset:1024 sc1
	global_store_dwordx2 v231, v[144:145], s[36:37] offset:1536 sc1
	v_lshlrev_b32_e32 v198, 16, v132
	v_and_b32_e32 v199, 0xffff0000, v132
	v_lshlrev_b32_e32 v200, 16, v133
	v_and_b32_e32 v201, 0xffff0000, v133
	v_lshlrev_b32_e32 v202, 16, v136
	v_and_b32_e32 v203, 0xffff0000, v136
	v_lshlrev_b32_e32 v204, 16, v137
	v_and_b32_e32 v205, 0xffff0000, v137
	v_lshlrev_b32_e32 v206, 16, v140
	v_and_b32_e32 v207, 0xffff0000, v140
	v_lshlrev_b32_e32 v72, 16, v141
	v_and_b32_e32 v73, 0xffff0000, v141
	v_lshlrev_b32_e32 v74, 16, v144
	v_and_b32_e32 v75, 0xffff0000, v144
	v_lshlrev_b32_e32 v78, 16, v145
	v_and_b32_e32 v79, 0xffff0000, v145
	v_mul_f32_e32 v228, v199, v199
	v_fma_f32 v228, v198, v198, v228
	v_mul_f32_e32 v229, v201, v201
	v_fma_f32 v229, v200, v200, v229
	v_add_f32_e32 v228, v228, v229
	v_mul_f32_e32 v229, v203, v203
	v_fma_f32 v229, v202, v202, v229
	v_mul_f32_e32 v227, v205, v205
	v_fma_f32 v227, v204, v204, v227
	v_add_f32_e32 v229, v229, v227
	v_add_f32_e32 v228, v228, v229
	v_mul_f32_e32 v229, v207, v207
	v_fma_f32 v229, v206, v206, v229
	v_mul_f32_e32 v227, v73, v73
	v_fma_f32 v227, v72, v72, v227
	v_add_f32_e32 v229, v229, v227
	v_add_f32_e32 v228, v228, v229
	v_mul_f32_e32 v229, v75, v75
	v_fma_f32 v229, v74, v74, v229
	v_mul_f32_e32 v227, v79, v79
	v_fma_f32 v227, v78, v78, v227
	v_add_f32_e32 v229, v229, v227
	v_add_f32_e32 v228, v228, v229
	s_nop 1
	v_add_f32_dpp v228, v228, v228 quad_perm:[1,0,3,2] row_mask:0xf bank_mask:0xf
	s_nop 1
	v_add_f32_dpp v228, v228, v228 quad_perm:[2,3,0,1] row_mask:0xf bank_mask:0xf
	s_nop 1
	v_add_f32_dpp v228, v228, v228 row_half_mirror row_mask:0xf bank_mask:0xf
	s_nop 1
	v_add_f32_dpp v228, v228, v228 row_mirror row_mask:0xf bank_mask:0xf
	s_nop 1
	v_add_f32_dpp v228, v228, v228 row_bcast:15 row_mask:0xa bank_mask:0xf
	s_nop 1
	v_add_f32_dpp v228, v228, v228 row_bcast:31 row_mask:0xc bank_mask:0xf
	s_nop 1
	v_readlane_b32 s4, v228, 63
	s_nop 1
	v_mov_b32_e32 v210, s4
	v_fmamk_f32 v210, v210, 0x3a800000, v209
	v_mul_f32_e32 v227, 0x4b800000, v210
	v_cmp_gt_f32_e32 vcc, s96, v210
	s_nop 1
	v_cndmask_b32_e32 v210, v210, v227, vcc
	v_rsq_f32_e32 v210, v210
	s_nop 0
	v_mul_f32_e32 v227, 0x45800000, v210
	v_cndmask_b32_e32 v210, v210, v227, vcc
	v_pk_mul_f32 v[198:199], v[210:211], v[198:199] op_sel_hi:[0,1]
	v_pk_fma_f32 v[198:199], v[32:33], v[198:199], v[56:57]
	v_pk_mul_f32 v[200:201], v[210:211], v[200:201] op_sel_hi:[0,1]
	v_pk_fma_f32 v[200:201], v[34:35], v[200:201], v[58:59]
	v_pk_mul_f32 v[202:203], v[210:211], v[202:203] op_sel_hi:[0,1]
	v_pk_fma_f32 v[202:203], v[36:37], v[202:203], v[60:61]
	v_pk_mul_f32 v[204:205], v[210:211], v[204:205] op_sel_hi:[0,1]
	v_pk_fma_f32 v[204:205], v[38:39], v[204:205], v[62:63]
	v_pk_mul_f32 v[206:207], v[210:211], v[206:207] op_sel_hi:[0,1]
	v_pk_fma_f32 v[206:207], v[40:41], v[206:207], v[64:65]
	v_pk_mul_f32 v[72:73], v[210:211], v[72:73] op_sel_hi:[0,1]
	v_pk_fma_f32 v[72:73], v[42:43], v[72:73], v[66:67]
	v_pk_mul_f32 v[74:75], v[210:211], v[74:75] op_sel_hi:[0,1]
	v_pk_fma_f32 v[74:75], v[44:45], v[74:75], v[68:69]
	v_pk_mul_f32 v[78:79], v[210:211], v[78:79] op_sel_hi:[0,1]
	v_pk_fma_f32 v[78:79], v[46:47], v[78:79], v[70:71]
	v_cvt_pk_bf16_f32 v134, v198, v199
	v_cvt_pk_bf16_f32 v135, v200, v201
	v_cvt_pk_bf16_f32 v138, v202, v203
	v_cvt_pk_bf16_f32 v139, v204, v205
	v_cvt_pk_bf16_f32 v142, v206, v207
	v_cvt_pk_bf16_f32 v143, v72, v73
	v_cvt_pk_bf16_f32 v146, v74, v75
	v_cvt_pk_bf16_f32 v147, v78, v79
	s_add_u32 s28, s10, 16777216
	s_addc_u32 s29, s11, 0
	global_store_dwordx2 v231, v[134:135], s[28:29] offset:0 sc1
	global_store_dwordx2 v231, v[138:139], s[28:29] offset:512 sc1
	global_store_dwordx2 v231, v[142:143], s[28:29] offset:1024 sc1
	global_store_dwordx2 v231, v[146:147], s[28:29] offset:1536 sc1
	s_add_u32 s22, s38, 58720256
	s_addc_u32 s23, s39, 0
	global_load_dwordx4 v[132:135], v172, s[22:23] offset:0 nt
	global_load_dwordx4 v[136:139], v172, s[22:23] offset:1024 nt
	global_load_dwordx4 v[140:143], v172, s[22:23] offset:2048 nt
	global_load_dwordx4 v[144:147], v172, s[22:23] offset:3072 nt
	s_waitcnt vmcnt(32)
; #define NORM_LOAD(V, ROW) do { const u32x2* xr_ = (const u32x2*)(X + (size_t)(ROW) * D); _Pragma("unroll") for (int j = 0; j < 4; ++j) { const u32x2 w_ = xr_[64 * j + lane]; \
;         V[j] = (f32x4){__uint_as_float(w_.x << 16), __uint_as_float(w_.x & 0xffff0000u), __uint_as_float(w_.y << 16), __uint_as_float(w_.y & 0xffff0000u)}; } } while (0)
; __device__ __forceinline__ void p_norm(const Args& a, int l, int lane, int wave, int bid, int G) {
;     ...
;     for (int row = MP + gw; row < M; row += NGW) {
;         const float* mp = mod + (size_t)(NPB + ((row - MP) >> 3)) * 3072;
;         f32x4 gs[4], sh[4], v0[4];
;         NORM_LOAD(v0, row);
; #pragma unroll
;         for (int j = 0; j < 4; ++j) { gs[j] = *((const f32x4*)g + 64 * j + lane) * (*((const f32x4*)(mp + D) + 64 * j + lane) + 1.0f); sh[j] = *((const f32x4*)mp + 64 * j + lane); }
;         NORM_FINISH(v0, row, gs, sh);
	v_cvt_pk_bf16_f32 v120, v120, v121
	v_cvt_pk_bf16_f32 v121, v122, v123
	v_cvt_pk_bf16_f32 v124, v124, v125
	v_cvt_pk_bf16_f32 v125, v126, v127
	v_cvt_pk_bf16_f32 v148, v148, v149
	v_cvt_pk_bf16_f32 v149, v150, v151
	v_cvt_pk_bf16_f32 v152, v152, v153
	v_cvt_pk_bf16_f32 v153, v154, v155
	s_add_u32 s36, s8, 20971520
	s_addc_u32 s37, s9, 0
	global_store_dwordx2 v231, v[120:121], s[36:37] offset:0 sc1
	global_store_dwordx2 v231, v[124:125], s[36:37] offset:512 sc1
	global_store_dwordx2 v231, v[148:149], s[36:37] offset:1024 sc1
	global_store_dwordx2 v231, v[152:153], s[36:37] offset:1536 sc1
	v_lshlrev_b32_e32 v198, 16, v120
	v_and_b32_e32 v199, 0xffff0000, v120
	v_lshlrev_b32_e32 v200, 16, v121
	v_and_b32_e32 v201, 0xffff0000, v121
	v_lshlrev_b32_e32 v202, 16, v124
	v_and_b32_e32 v203, 0xffff0000, v124
	v_lshlrev_b32_e32 v204, 16, v125
	v_and_b32_e32 v205, 0xffff0000, v125
	v_lshlrev_b32_e32 v206, 16, v148
	v_and_b32_e32 v207, 0xffff0000, v148
	v_lshlrev_b32_e32 v72, 16, v149
	v_and_b32_e32 v73, 0xffff0000, v149
	v_lshlrev_b32_e32 v74, 16, v152
	v_and_b32_e32 v75, 0xffff0000, v152
	v_lshlrev_b32_e32 v78, 16, v153
	v_and_b32_e32 v79, 0xffff0000, v153
	v_mul_f32_e32 v228, v199, v199
	v_fma_f32 v228, v198, v198, v228
	v_mul_f32_e32 v229, v201, v201
	v_fma_f32 v229, v200, v200, v229
	v_add_f32_e32 v228, v228, v229
	v_mul_f32_e32 v229, v203, v203
	v_fma_f32 v229, v202, v202, v229
	v_mul_f32_e32 v227, v205, v205
	v_fma_f32 v227, v204, v204, v227
	v_add_f32_e32 v229, v229, v227
	v_add_f32_e32 v228, v228, v229
	v_mul_f32_e32 v229, v207, v207
	v_fma_f32 v229, v206, v206, v229
	v_mul_f32_e32 v227, v73, v73
	v_fma_f32 v227, v72, v72, v227
	v_add_f32_e32 v229, v229, v227
	v_add_f32_e32 v228, v228, v229
	v_mul_f32_e32 v229, v75, v75
	v_fma_f32 v229, v74, v74, v229
	v_mul_f32_e32 v227, v79, v79
	v_fma_f32 v227, v78, v78, v227
	v_add_f32_e32 v229, v229, v227
	v_add_f32_e32 v228, v228, v229
	s_nop 1
	v_add_f32_dpp v228, v228, v228 quad_perm:[1,0,3,2] row_mask:0xf bank_mask:0xf
	s_nop 1
	v_add_f32_dpp v228, v228, v228 quad_perm:[2,3,0,1] row_mask:0xf bank_mask:0xf
	s_nop 1
	v_add_f32_dpp v228, v228, v228 row_half_mirror row_mask:0xf bank_mask:0xf
	s_nop 1
	v_add_f32_dpp v228, v228, v228 row_mirror row_mask:0xf bank_mask:0xf
	s_nop 1
	v_add_f32_dpp v228, v228, v228 row_bcast:15 row_mask:0xa bank_mask:0xf
	s_nop 1
	v_add_f32_dpp v228, v228, v228 row_bcast:31 row_mask:0xc bank_mask:0xf
	s_nop 1
	v_readlane_b32 s4, v228, 63
	s_nop 1
	v_mov_b32_e32 v210, s4
	v_fmamk_f32 v210, v210, 0x3a800000, v209
	v_mul_f32_e32 v227, 0x4b800000, v210
	v_cmp_gt_f32_e32 vcc, s96, v210
	s_nop 1
	v_cndmask_b32_e32 v210, v210, v227, vcc
	v_rsq_f32_e32 v210, v210
	s_nop 0
	v_mul_f32_e32 v227, 0x45800000, v210
	v_cndmask_b32_e32 v210, v210, v227, vcc
	v_pk_mul_f32 v[198:199], v[210:211], v[198:199] op_sel_hi:[0,1]
	v_pk_fma_f32 v[198:199], v[32:33], v[198:199], v[56:57]
	v_pk_mul_f32 v[200:201], v[210:211], v[200:201] op_sel_hi:[0,1]
	v_pk_fma_f32 v[200:201], v[34:35], v[200:201], v[58:59]
	v_pk_mul_f32 v[202:203], v[210:211], v[202:203] op_sel_hi:[0,1]
	v_pk_fma_f32 v[202:203], v[36:37], v[202:203], v[60:61]
	v_pk_mul_f32 v[204:205], v[210:211], v[204:205] op_sel_hi:[0,1]
	v_pk_fma_f32 v[204:205], v[38:39], v[204:205], v[62:63]
	v_pk_mul_f32 v[206:207], v[210:211], v[206:207] op_sel_hi:[0,1]
	v_pk_fma_f32 v[206:207], v[40:41], v[206:207], v[64:65]
	v_pk_mul_f32 v[72:73], v[210:211], v[72:73] op_sel_hi:[0,1]
	v_pk_fma_f32 v[72:73], v[42:43], v[72:73], v[66:67]
	v_pk_mul_f32 v[74:75], v[210:211], v[74:75] op_sel_hi:[0,1]
	v_pk_fma_f32 v[74:75], v[44:45], v[74:75], v[68:69]
	v_pk_mul_f32 v[78:79], v[210:211], v[78:79] op_sel_hi:[0,1]
	v_pk_fma_f32 v[78:79], v[46:47], v[78:79], v[70:71]
	v_cvt_pk_bf16_f32 v122, v198, v199
	v_cvt_pk_bf16_f32 v123, v200, v201
	v_cvt_pk_bf16_f32 v126, v202, v203
	v_cvt_pk_bf16_f32 v127, v204, v205
	v_cvt_pk_bf16_f32 v150, v206, v207
	v_cvt_pk_bf16_f32 v151, v72, v73
	v_cvt_pk_bf16_f32 v154, v74, v75
	v_cvt_pk_bf16_f32 v155, v78, v79
	s_add_u32 s28, s10, 20971520
	s_addc_u32 s29, s11, 0
	global_store_dwordx2 v231, v[122:123], s[28:29] offset:0 sc1
	global_store_dwordx2 v231, v[126:127], s[28:29] offset:512 sc1
	global_store_dwordx2 v231, v[150:151], s[28:29] offset:1024 sc1
	global_store_dwordx2 v231, v[154:155], s[28:29] offset:1536 sc1
	global_load_dwordx4 v[120:123], v172, s[52:53] offset:0 nt
	global_load_dwordx4 v[124:127], v172, s[52:53] offset:1024 nt
	global_load_dwordx4 v[148:151], v172, s[52:53] offset:2048 nt
	global_load_dwordx4 v[152:155], v172, s[52:53] offset:3072 nt
	s_waitcnt vmcnt(24)
	v_pk_add_f32 v[156:157], v[156:157], 1.0 op_sel_hi:[1,0]
	v_pk_add_f32 v[158:159], v[158:159], 1.0 op_sel_hi:[1,0]
	v_pk_add_f32 v[160:161], v[160:161], 1.0 op_sel_hi:[1,0]
	v_pk_add_f32 v[162:163], v[162:163], 1.0 op_sel_hi:[1,0]
	v_pk_add_f32 v[164:165], v[164:165], 1.0 op_sel_hi:[1,0]
	v_pk_add_f32 v[166:167], v[166:167], 1.0 op_sel_hi:[1,0]
	v_pk_add_f32 v[168:169], v[168:169], 1.0 op_sel_hi:[1,0]
	v_pk_add_f32 v[170:171], v[170:171], 1.0 op_sel_hi:[1,0]
	v_pk_mul_f32 v[156:157], v[236:237], v[156:157]
	v_pk_mul_f32 v[158:159], v[238:239], v[158:159]
	v_pk_mul_f32 v[160:161], v[240:241], v[160:161]
	v_pk_mul_f32 v[162:163], v[242:243], v[162:163]
	v_pk_mul_f32 v[164:165], v[244:245], v[164:165]
	v_pk_mul_f32 v[166:167], v[246:247], v[166:167]
	v_pk_mul_f32 v[168:169], v[248:249], v[168:169]
	v_pk_mul_f32 v[170:171], v[250:251], v[170:171]
	s_lshr_b32 s21, s0, 3
	s_add_i32 s21, s21, 4
	s_mul_i32 s21, s21, 0x3000
	s_add_u32 s30, s2, s21
	s_addc_u32 s31, s3, 0
	s_add_u32 s34, s30, 0x1000
	s_addc_u32 s35, s31, 0
	global_load_dwordx4 v[32:35], v172, s[34:35] offset:0
	global_load_dwordx4 v[36:39], v172, s[34:35] offset:1024
	global_load_dwordx4 v[40:43], v172, s[34:35] offset:2048
	global_load_dwordx4 v[44:47], v172, s[34:35] offset:3072
	global_load_dwordx4 v[56:59], v172, s[30:31] offset:0
	global_load_dwordx4 v[60:63], v172, s[30:31] offset:1024
	global_load_dwordx4 v[64:67], v172, s[30:31] offset:2048
	global_load_dwordx4 v[68:71], v172, s[30:31] offset:3072
	s_waitcnt vmcnt(40)
; #define NORM_LOAD(V, ROW) do { const u32x2* xr_ = (const u32x2*)(X + (size_t)(ROW) * D); _Pragma("unroll") for (int j = 0; j < 4; ++j) { const u32x2 w_ = xr_[64 * j + lane]; \
;         V[j] = (f32x4){__uint_as_float(w_.x << 16), __uint_as_float(w_.x & 0xffff0000u), __uint_as_float(w_.y << 16), __uint_as_float(w_.y & 0xffff0000u)}; } } while (0)
; __device__ __forceinline__ void p_norm(const Args& a, int l, int lane, int wave, int bid, int G) {
;     ...
;         f32x4 gs[4], sh[4];
; #pragma unroll
;         for (int j = 0; j < 4; ++j) { gs[j] = *((const f32x4*)g + 64 * j + lane) * (*((const f32x4*)(mp + D) + 64 * j + lane) + 1.0f); sh[j] = *((const f32x4*)mp + 64 * j + lane); }
; #pragma unroll 1
;         for (int r0 = gw; r0 < LP; r0 += 3 * NGW) {
;             f32x4 v0[4], v1[4], v2[4];
;             const int ra = n * LP + r0, rb = ra + NGW, rc = rb + NGW;
;             const bool hb = r0 + NGW < LP, hc = r0 + 2 * NGW < LP;
;             NORM_LOAD(v0, ra); if (hb) NORM_LOAD(v1, rb); if (hc) NORM_LOAD(v2, rc);
;             NORM_FINISH(v0, ra, gs, sh); if (hb) NORM_FINISH(v1, rb, gs, sh); if (hc) NORM_FINISH(v2, rc, gs, sh);
	v_cvt_pk_bf16_f32 v104, v104, v105
	v_cvt_pk_bf16_f32 v105, v106, v107
	v_cvt_pk_bf16_f32 v108, v108, v109
	v_cvt_pk_bf16_f32 v109, v110, v111
	v_cvt_pk_bf16_f32 v112, v112, v113
	v_cvt_pk_bf16_f32 v113, v114, v115
	v_cvt_pk_bf16_f32 v116, v116, v117
	v_cvt_pk_bf16_f32 v117, v118, v119
	s_add_u32 s36, s8, 25165824
	s_addc_u32 s37, s9, 0
	global_store_dwordx2 v231, v[104:105], s[36:37] offset:0 sc1
	global_store_dwordx2 v231, v[108:109], s[36:37] offset:512 sc1
	global_store_dwordx2 v231, v[112:113], s[36:37] offset:1024 sc1
	global_store_dwordx2 v231, v[116:117], s[36:37] offset:1536 sc1
	v_lshlrev_b32_e32 v198, 16, v104
	v_and_b32_e32 v199, 0xffff0000, v104
	v_lshlrev_b32_e32 v200, 16, v105
	v_and_b32_e32 v201, 0xffff0000, v105
	v_lshlrev_b32_e32 v202, 16, v108
	v_and_b32_e32 v203, 0xffff0000, v108
	v_lshlrev_b32_e32 v204, 16, v109
	v_and_b32_e32 v205, 0xffff0000, v109
	v_lshlrev_b32_e32 v206, 16, v112
	v_and_b32_e32 v207, 0xffff0000, v112
	v_lshlrev_b32_e32 v72, 16, v113
	v_and_b32_e32 v73, 0xffff0000, v113
	v_lshlrev_b32_e32 v74, 16, v116
	v_and_b32_e32 v75, 0xffff0000, v116
	v_lshlrev_b32_e32 v78, 16, v117
	v_and_b32_e32 v79, 0xffff0000, v117
	v_mul_f32_e32 v228, v199, v199
	v_fma_f32 v228, v198, v198, v228
	v_mul_f32_e32 v229, v201, v201
	v_fma_f32 v229, v200, v200, v229
	v_add_f32_e32 v228, v228, v229
	v_mul_f32_e32 v229, v203, v203
	v_fma_f32 v229, v202, v202, v229
	v_mul_f32_e32 v227, v205, v205
	v_fma_f32 v227, v204, v204, v227
	v_add_f32_e32 v229, v229, v227
	v_add_f32_e32 v228, v228, v229
	v_mul_f32_e32 v229, v207, v207
	v_fma_f32 v229, v206, v206, v229
	v_mul_f32_e32 v227, v73, v73
	v_fma_f32 v227, v72, v72, v227
	v_add_f32_e32 v229, v229, v227
	v_add_f32_e32 v228, v228, v229
	v_mul_f32_e32 v229, v75, v75
	v_fma_f32 v229, v74, v74, v229
	v_mul_f32_e32 v227, v79, v79
	v_fma_f32 v227, v78, v78, v227
	v_add_f32_e32 v229, v229, v227
	v_add_f32_e32 v228, v228, v229
	s_nop 1
	v_add_f32_dpp v228, v228, v228 quad_perm:[1,0,3,2] row_mask:0xf bank_mask:0xf
	s_nop 1
	v_add_f32_dpp v228, v228, v228 quad_perm:[2,3,0,1] row_mask:0xf bank_mask:0xf
	s_nop 1
	v_add_f32_dpp v228, v228, v228 row_half_mirror row_mask:0xf bank_mask:0xf
	s_nop 1
	v_add_f32_dpp v228, v228, v228 row_mirror row_mask:0xf bank_mask:0xf
	s_nop 1
	v_add_f32_dpp v228, v228, v228 row_bcast:15 row_mask:0xa bank_mask:0xf
	s_nop 1
	v_add_f32_dpp v228, v228, v228 row_bcast:31 row_mask:0xc bank_mask:0xf
	s_nop 1
	v_readlane_b32 s4, v228, 63
	s_nop 1
	v_mov_b32_e32 v210, s4
	v_fmamk_f32 v210, v210, 0x3a800000, v209
	v_mul_f32_e32 v227, 0x4b800000, v210
	v_cmp_gt_f32_e32 vcc, s96, v210
	s_nop 1
	v_cndmask_b32_e32 v210, v210, v227, vcc
	v_rsq_f32_e32 v210, v210
	s_nop 0
	v_mul_f32_e32 v227, 0x45800000, v210
	v_cndmask_b32_e32 v210, v210, v227, vcc
	v_pk_mul_f32 v[198:199], v[210:211], v[198:199] op_sel_hi:[0,1]
	v_pk_fma_f32 v[198:199], v[156:157], v[198:199], v[182:183]
	v_pk_mul_f32 v[200:201], v[210:211], v[200:201] op_sel_hi:[0,1]
	v_pk_fma_f32 v[200:201], v[158:159], v[200:201], v[184:185]
	v_pk_mul_f32 v[202:203], v[210:211], v[202:203] op_sel_hi:[0,1]
	v_pk_fma_f32 v[202:203], v[160:161], v[202:203], v[186:187]
	v_pk_mul_f32 v[204:205], v[210:211], v[204:205] op_sel_hi:[0,1]
	v_pk_fma_f32 v[204:205], v[162:163], v[204:205], v[188:189]
	v_pk_mul_f32 v[206:207], v[210:211], v[206:207] op_sel_hi:[0,1]
	v_pk_fma_f32 v[206:207], v[164:165], v[206:207], v[190:191]
	v_pk_mul_f32 v[72:73], v[210:211], v[72:73] op_sel_hi:[0,1]
	v_pk_fma_f32 v[72:73], v[166:167], v[72:73], v[192:193]
	v_pk_mul_f32 v[74:75], v[210:211], v[74:75] op_sel_hi:[0,1]
	v_pk_fma_f32 v[74:75], v[168:169], v[74:75], v[194:195]
	v_pk_mul_f32 v[78:79], v[210:211], v[78:79] op_sel_hi:[0,1]
	v_pk_fma_f32 v[78:79], v[170:171], v[78:79], v[196:197]
	v_cvt_pk_bf16_f32 v106, v198, v199
	v_cvt_pk_bf16_f32 v107, v200, v201
	v_cvt_pk_bf16_f32 v110, v202, v203
	v_cvt_pk_bf16_f32 v111, v204, v205
	v_cvt_pk_bf16_f32 v114, v206, v207
	v_cvt_pk_bf16_f32 v115, v72, v73
	v_cvt_pk_bf16_f32 v118, v74, v75
	v_cvt_pk_bf16_f32 v119, v78, v79
	s_add_u32 s28, s10, 25165824
	s_addc_u32 s29, s11, 0
	global_store_dwordx2 v231, v[106:107], s[28:29] offset:0 sc1
	global_store_dwordx2 v231, v[110:111], s[28:29] offset:512 sc1
	global_store_dwordx2 v231, v[114:115], s[28:29] offset:1024 sc1
	global_store_dwordx2 v231, v[118:119], s[28:29] offset:1536 sc1
	s_waitcnt vmcnt(28)
; #define NORM_LOAD(V, ROW) do { const u32x2* xr_ = (const u32x2*)(X + (size_t)(ROW) * D); _Pragma("unroll") for (int j = 0; j < 4; ++j) { const u32x2 w_ = xr_[64 * j + lane]; \
;         V[j] = (f32x4){__uint_as_float(w_.x << 16), __uint_as_float(w_.x & 0xffff0000u), __uint_as_float(w_.y << 16), __uint_as_float(w_.y & 0xffff0000u)}; } } while (0)
; __device__ __forceinline__ void p_norm(const Args& a, int l, int lane, int wave, int bid, int G) {
;     ...
;         f32x4 gs[4], sh[4];
; #pragma unroll
;         for (int j = 0; j < 4; ++j) { gs[j] = *((const f32x4*)g + 64 * j + lane) * (*((const f32x4*)(mp + D) + 64 * j + lane) + 1.0f); sh[j] = *((const f32x4*)mp + 64 * j + lane); }
; #pragma unroll 1
;         for (int r0 = gw; r0 < LP; r0 += 3 * NGW) {
;             f32x4 v0[4], v1[4], v2[4];
;             const int ra = n * LP + r0, rb = ra + NGW, rc = rb + NGW;
;             const bool hb = r0 + NGW < LP, hc = r0 + 2 * NGW < LP;
;             NORM_LOAD(v0, ra); if (hb) NORM_LOAD(v1, rb); if (hc) NORM_LOAD(v2, rc);
;             NORM_FINISH(v0, ra, gs, sh); if (hb) NORM_FINISH(v1, rb, gs, sh); if (hc) NORM_FINISH(v2, rc, gs, sh);
	v_cvt_pk_bf16_f32 v132, v132, v133
	v_cvt_pk_bf16_f32 v133, v134, v135
	v_cvt_pk_bf16_f32 v136, v136, v137
	v_cvt_pk_bf16_f32 v137, v138, v139
	v_cvt_pk_bf16_f32 v140, v140, v141
	v_cvt_pk_bf16_f32 v141, v142, v143
	v_cvt_pk_bf16_f32 v144, v144, v145
	v_cvt_pk_bf16_f32 v145, v146, v147
	s_add_u32 s36, s8, 29360128
	s_addc_u32 s37, s9, 0
	global_store_dwordx2 v231, v[132:133], s[36:37] offset:0 sc1
	global_store_dwordx2 v231, v[136:137], s[36:37] offset:512 sc1
	global_store_dwordx2 v231, v[140:141], s[36:37] offset:1024 sc1
	global_store_dwordx2 v231, v[144:145], s[36:37] offset:1536 sc1
	v_lshlrev_b32_e32 v198, 16, v132
	v_and_b32_e32 v199, 0xffff0000, v132
	v_lshlrev_b32_e32 v200, 16, v133
	v_and_b32_e32 v201, 0xffff0000, v133
	v_lshlrev_b32_e32 v202, 16, v136
	v_and_b32_e32 v203, 0xffff0000, v136
	v_lshlrev_b32_e32 v204, 16, v137
	v_and_b32_e32 v205, 0xffff0000, v137
	v_lshlrev_b32_e32 v206, 16, v140
	v_and_b32_e32 v207, 0xffff0000, v140
	v_lshlrev_b32_e32 v72, 16, v141
	v_and_b32_e32 v73, 0xffff0000, v141
	v_lshlrev_b32_e32 v74, 16, v144
	v_and_b32_e32 v75, 0xffff0000, v144
	v_lshlrev_b32_e32 v78, 16, v145
	v_and_b32_e32 v79, 0xffff0000, v145
	v_mul_f32_e32 v228, v199, v199
	v_fma_f32 v228, v198, v198, v228
	v_mul_f32_e32 v229, v201, v201
	v_fma_f32 v229, v200, v200, v229
	v_add_f32_e32 v228, v228, v229
	v_mul_f32_e32 v229, v203, v203
	v_fma_f32 v229, v202, v202, v229
	v_mul_f32_e32 v227, v205, v205
	v_fma_f32 v227, v204, v204, v227
	v_add_f32_e32 v229, v229, v227
	v_add_f32_e32 v228, v228, v229
	v_mul_f32_e32 v229, v207, v207
	v_fma_f32 v229, v206, v206, v229
	v_mul_f32_e32 v227, v73, v73
	v_fma_f32 v227, v72, v72, v227
	v_add_f32_e32 v229, v229, v227
	v_add_f32_e32 v228, v228, v229
	v_mul_f32_e32 v229, v75, v75
	v_fma_f32 v229, v74, v74, v229
	v_mul_f32_e32 v227, v79, v79
	v_fma_f32 v227, v78, v78, v227
	v_add_f32_e32 v229, v229, v227
	v_add_f32_e32 v228, v228, v229
	s_nop 1
	v_add_f32_dpp v228, v228, v228 quad_perm:[1,0,3,2] row_mask:0xf bank_mask:0xf
	s_nop 1
	v_add_f32_dpp v228, v228, v228 quad_perm:[2,3,0,1] row_mask:0xf bank_mask:0xf
	s_nop 1
	v_add_f32_dpp v228, v228, v228 row_half_mirror row_mask:0xf bank_mask:0xf
	s_nop 1
	v_add_f32_dpp v228, v228, v228 row_mirror row_mask:0xf bank_mask:0xf
	s_nop 1
	v_add_f32_dpp v228, v228, v228 row_bcast:15 row_mask:0xa bank_mask:0xf
	s_nop 1
	v_add_f32_dpp v228, v228, v228 row_bcast:31 row_mask:0xc bank_mask:0xf
	s_nop 1
	v_readlane_b32 s4, v228, 63
	s_nop 1
	v_mov_b32_e32 v210, s4
	v_fmamk_f32 v210, v210, 0x3a800000, v209
	v_mul_f32_e32 v227, 0x4b800000, v210
	v_cmp_gt_f32_e32 vcc, s96, v210
	s_nop 1
	v_cndmask_b32_e32 v210, v210, v227, vcc
	v_rsq_f32_e32 v210, v210
	s_nop 0
	v_mul_f32_e32 v227, 0x45800000, v210
	v_cndmask_b32_e32 v210, v210, v227, vcc
	v_pk_mul_f32 v[198:199], v[210:211], v[198:199] op_sel_hi:[0,1]
	v_pk_fma_f32 v[198:199], v[156:157], v[198:199], v[182:183]
	v_pk_mul_f32 v[200:201], v[210:211], v[200:201] op_sel_hi:[0,1]
	v_pk_fma_f32 v[200:201], v[158:159], v[200:201], v[184:185]
	v_pk_mul_f32 v[202:203], v[210:211], v[202:203] op_sel_hi:[0,1]
	v_pk_fma_f32 v[202:203], v[160:161], v[202:203], v[186:187]
	v_pk_mul_f32 v[204:205], v[210:211], v[204:205] op_sel_hi:[0,1]
	v_pk_fma_f32 v[204:205], v[162:163], v[204:205], v[188:189]
	v_pk_mul_f32 v[206:207], v[210:211], v[206:207] op_sel_hi:[0,1]
	v_pk_fma_f32 v[206:207], v[164:165], v[206:207], v[190:191]
	v_pk_mul_f32 v[72:73], v[210:211], v[72:73] op_sel_hi:[0,1]
	v_pk_fma_f32 v[72:73], v[166:167], v[72:73], v[192:193]
	v_pk_mul_f32 v[74:75], v[210:211], v[74:75] op_sel_hi:[0,1]
	v_pk_fma_f32 v[74:75], v[168:169], v[74:75], v[194:195]
	v_pk_mul_f32 v[78:79], v[210:211], v[78:79] op_sel_hi:[0,1]
	v_pk_fma_f32 v[78:79], v[170:171], v[78:79], v[196:197]
	v_cvt_pk_bf16_f32 v134, v198, v199
	v_cvt_pk_bf16_f32 v135, v200, v201
	v_cvt_pk_bf16_f32 v138, v202, v203
	v_cvt_pk_bf16_f32 v139, v204, v205
	v_cvt_pk_bf16_f32 v142, v206, v207
	v_cvt_pk_bf16_f32 v143, v72, v73
	v_cvt_pk_bf16_f32 v146, v74, v75
	v_cvt_pk_bf16_f32 v147, v78, v79
	s_add_u32 s28, s10, 29360128
	s_addc_u32 s29, s11, 0
	global_store_dwordx2 v231, v[134:135], s[28:29] offset:0 sc1
	global_store_dwordx2 v231, v[138:139], s[28:29] offset:512 sc1
	global_store_dwordx2 v231, v[142:143], s[28:29] offset:1024 sc1
	global_store_dwordx2 v231, v[146:147], s[28:29] offset:1536 sc1
	s_waitcnt vmcnt(16)
	v_pk_add_f32 v[32:33], v[32:33], 1.0 op_sel_hi:[1,0]
	v_pk_add_f32 v[34:35], v[34:35], 1.0 op_sel_hi:[1,0]
	v_pk_add_f32 v[36:37], v[36:37], 1.0 op_sel_hi:[1,0]
	v_pk_add_f32 v[38:39], v[38:39], 1.0 op_sel_hi:[1,0]
	v_pk_add_f32 v[40:41], v[40:41], 1.0 op_sel_hi:[1,0]
	v_pk_add_f32 v[42:43], v[42:43], 1.0 op_sel_hi:[1,0]
	v_pk_add_f32 v[44:45], v[44:45], 1.0 op_sel_hi:[1,0]
	v_pk_add_f32 v[46:47], v[46:47], 1.0 op_sel_hi:[1,0]
	v_pk_mul_f32 v[32:33], v[236:237], v[32:33]
	v_pk_mul_f32 v[34:35], v[238:239], v[34:35]
	v_pk_mul_f32 v[36:37], v[240:241], v[36:37]
	v_pk_mul_f32 v[38:39], v[242:243], v[38:39]
	v_pk_mul_f32 v[40:41], v[244:245], v[40:41]
	v_pk_mul_f32 v[42:43], v[246:247], v[42:43]
	v_pk_mul_f32 v[44:45], v[248:249], v[44:45]
	v_pk_mul_f32 v[46:47], v[250:251], v[46:47]
	s_waitcnt vmcnt(24)
; #define NORM_LOAD(V, ROW) do { const u32x2* xr_ = (const u32x2*)(X + (size_t)(ROW) * D); _Pragma("unroll") for (int j = 0; j < 4; ++j) { const u32x2 w_ = xr_[64 * j + lane]; \
;         V[j] = (f32x4){__uint_as_float(w_.x << 16), __uint_as_float(w_.x & 0xffff0000u), __uint_as_float(w_.y << 16), __uint_as_float(w_.y & 0xffff0000u)}; } } while (0)
; __device__ __forceinline__ void p_norm(const Args& a, int l, int lane, int wave, int bid, int G) {
;     ...
;     for (int row = MP + gw; row < M; row += NGW) {
;         const float* mp = mod + (size_t)(NPB + ((row - MP) >> 3)) * 3072;
;         f32x4 gs[4], sh[4], v0[4];
;         NORM_LOAD(v0, row);
; #pragma unroll
;         for (int j = 0; j < 4; ++j) { gs[j] = *((const f32x4*)g + 64 * j + lane) * (*((const f32x4*)(mp + D) + 64 * j + lane) + 1.0f); sh[j] = *((const f32x4*)mp + 64 * j + lane); }
;         NORM_FINISH(v0, row, gs, sh);
	v_cvt_pk_bf16_f32 v120, v120, v121
	v_cvt_pk_bf16_f32 v121, v122, v123
	v_cvt_pk_bf16_f32 v124, v124, v125
	v_cvt_pk_bf16_f32 v125, v126, v127
	v_cvt_pk_bf16_f32 v148, v148, v149
	v_cvt_pk_bf16_f32 v149, v150, v151
	v_cvt_pk_bf16_f32 v152, v152, v153
	v_cvt_pk_bf16_f32 v153, v154, v155
	s_add_u32 s36, s8, 33554432
	s_addc_u32 s37, s9, 0
	global_store_dwordx2 v231, v[120:121], s[36:37] offset:0 sc1
	global_store_dwordx2 v231, v[124:125], s[36:37] offset:512 sc1
	global_store_dwordx2 v231, v[148:149], s[36:37] offset:1024 sc1
	global_store_dwordx2 v231, v[152:153], s[36:37] offset:1536 sc1
	v_lshlrev_b32_e32 v198, 16, v120
	v_and_b32_e32 v199, 0xffff0000, v120
	v_lshlrev_b32_e32 v200, 16, v121
	v_and_b32_e32 v201, 0xffff0000, v121
	v_lshlrev_b32_e32 v202, 16, v124
	v_and_b32_e32 v203, 0xffff0000, v124
	v_lshlrev_b32_e32 v204, 16, v125
	v_and_b32_e32 v205, 0xffff0000, v125
	v_lshlrev_b32_e32 v206, 16, v148
	v_and_b32_e32 v207, 0xffff0000, v148
	v_lshlrev_b32_e32 v72, 16, v149
	v_and_b32_e32 v73, 0xffff0000, v149
	v_lshlrev_b32_e32 v74, 16, v152
	v_and_b32_e32 v75, 0xffff0000, v152
	v_lshlrev_b32_e32 v78, 16, v153
	v_and_b32_e32 v79, 0xffff0000, v153
	v_mul_f32_e32 v228, v199, v199
	v_fma_f32 v228, v198, v198, v228
	v_mul_f32_e32 v229, v201, v201
	v_fma_f32 v229, v200, v200, v229
	v_add_f32_e32 v228, v228, v229
	v_mul_f32_e32 v229, v203, v203
	v_fma_f32 v229, v202, v202, v229
	v_mul_f32_e32 v227, v205, v205
	v_fma_f32 v227, v204, v204, v227
	v_add_f32_e32 v229, v229, v227
	v_add_f32_e32 v228, v228, v229
	v_mul_f32_e32 v229, v207, v207
	v_fma_f32 v229, v206, v206, v229
	v_mul_f32_e32 v227, v73, v73
	v_fma_f32 v227, v72, v72, v227
	v_add_f32_e32 v229, v229, v227
	v_add_f32_e32 v228, v228, v229
	v_mul_f32_e32 v229, v75, v75
	v_fma_f32 v229, v74, v74, v229
	v_mul_f32_e32 v227, v79, v79
	v_fma_f32 v227, v78, v78, v227
	v_add_f32_e32 v229, v229, v227
	v_add_f32_e32 v228, v228, v229
	s_nop 1
	v_add_f32_dpp v228, v228, v228 quad_perm:[1,0,3,2] row_mask:0xf bank_mask:0xf
	s_nop 1
	v_add_f32_dpp v228, v228, v228 quad_perm:[2,3,0,1] row_mask:0xf bank_mask:0xf
	s_nop 1
	v_add_f32_dpp v228, v228, v228 row_half_mirror row_mask:0xf bank_mask:0xf
	s_nop 1
	v_add_f32_dpp v228, v228, v228 row_mirror row_mask:0xf bank_mask:0xf
	s_nop 1
	v_add_f32_dpp v228, v228, v228 row_bcast:15 row_mask:0xa bank_mask:0xf
	s_nop 1
	v_add_f32_dpp v228, v228, v228 row_bcast:31 row_mask:0xc bank_mask:0xf
	s_nop 1
	v_readlane_b32 s4, v228, 63
	s_nop 1
	v_mov_b32_e32 v210, s4
	v_fmamk_f32 v210, v210, 0x3a800000, v209
	v_mul_f32_e32 v227, 0x4b800000, v210
	v_cmp_gt_f32_e32 vcc, s96, v210
	s_nop 1
	v_cndmask_b32_e32 v210, v210, v227, vcc
	v_rsq_f32_e32 v210, v210
	s_nop 0
	v_mul_f32_e32 v227, 0x45800000, v210
	v_cndmask_b32_e32 v210, v210, v227, vcc
	v_pk_mul_f32 v[198:199], v[210:211], v[198:199] op_sel_hi:[0,1]
	v_pk_fma_f32 v[198:199], v[32:33], v[198:199], v[56:57]
	v_pk_mul_f32 v[200:201], v[210:211], v[200:201] op_sel_hi:[0,1]
	v_pk_fma_f32 v[200:201], v[34:35], v[200:201], v[58:59]
	v_pk_mul_f32 v[202:203], v[210:211], v[202:203] op_sel_hi:[0,1]
	v_pk_fma_f32 v[202:203], v[36:37], v[202:203], v[60:61]
	v_pk_mul_f32 v[204:205], v[210:211], v[204:205] op_sel_hi:[0,1]
	v_pk_fma_f32 v[204:205], v[38:39], v[204:205], v[62:63]
	v_pk_mul_f32 v[206:207], v[210:211], v[206:207] op_sel_hi:[0,1]
	v_pk_fma_f32 v[206:207], v[40:41], v[206:207], v[64:65]
	v_pk_mul_f32 v[72:73], v[210:211], v[72:73] op_sel_hi:[0,1]
	v_pk_fma_f32 v[72:73], v[42:43], v[72:73], v[66:67]
	v_pk_mul_f32 v[74:75], v[210:211], v[74:75] op_sel_hi:[0,1]
	v_pk_fma_f32 v[74:75], v[44:45], v[74:75], v[68:69]
	v_pk_mul_f32 v[78:79], v[210:211], v[78:79] op_sel_hi:[0,1]
	v_pk_fma_f32 v[78:79], v[46:47], v[78:79], v[70:71]
	v_cvt_pk_bf16_f32 v122, v198, v199
	v_cvt_pk_bf16_f32 v123, v200, v201
	v_cvt_pk_bf16_f32 v126, v202, v203
	v_cvt_pk_bf16_f32 v127, v204, v205
	v_cvt_pk_bf16_f32 v150, v206, v207
	v_cvt_pk_bf16_f32 v151, v72, v73
	v_cvt_pk_bf16_f32 v154, v74, v75
	v_cvt_pk_bf16_f32 v155, v78, v79
	s_add_u32 s28, s10, 33554432
	s_addc_u32 s29, s11, 0
	global_store_dwordx2 v231, v[122:123], s[28:29] offset:0 sc1
	global_store_dwordx2 v231, v[126:127], s[28:29] offset:512 sc1
	global_store_dwordx2 v231, v[150:151], s[28:29] offset:1024 sc1
	global_store_dwordx2 v231, v[154:155], s[28:29] offset:1536 sc1
	v_lshlrev_b32_e32 v172, 4, v50
	s_branch .LBB0_207
; #define NORM_LOAD(V, ROW) do { const u32x2* xr_ = (const u32x2*)(X + (size_t)(ROW) * D); _Pragma("unroll") for (int j = 0; j < 4; ++j) { const u32x2 w_ = xr_[64 * j + lane]; \
;         V[j] = (f32x4){__uint_as_float(w_.x << 16), __uint_as_float(w_.x & 0xffff0000u), __uint_as_float(w_.y << 16), __uint_as_float(w_.y & 0xffff0000u)}; } } while (0)
; __device__ __forceinline__ void p_norm(const Args& a, int l, int lane, int wave, int bid, int G) {
;     ...
; #pragma unroll 1
;     for (int n = 0; n < NPB; ++n) {
;         const float* mp = mod + (size_t)n * 3072;
;         f32x4 gs[4], sh[4];
; #pragma unroll
;         for (int j = 0; j < 4; ++j) { gs[j] = *((const f32x4*)g + 64 * j + lane) * (*((const f32x4*)(mp + D) + 64 * j + lane) + 1.0f); sh[j] = *((const f32x4*)mp + 64 * j + lane); }
; #pragma unroll 1
;         for (int r0 = gw; r0 < LP; r0 += 3 * NGW) {
;             f32x4 v0[4], v1[4], v2[4];
;             const int ra = n * LP + r0, rb = ra + NGW, rc = rb + NGW;
;             const bool hb = r0 + NGW < LP, hc = r0 + 2 * NGW < LP;
;             NORM_LOAD(v0, ra); if (hb) NORM_LOAD(v1, rb); if (hc) NORM_LOAD(v2, rc);
;             NORM_FINISH(v0, ra, gs, sh); if (hb) NORM_FINISH(v1, rb, gs, sh); if (hc) NORM_FINISH(v2, rc, gs, sh);
.Lnorm0_b:
	global_load_dwordx4 v[236:239], v[48:49], off offset:0
	global_load_dwordx4 v[240:243], v[48:49], off offset:1024
	global_load_dwordx4 v[244:247], v[48:49], off offset:2048
	global_load_dwordx4 v[248:251], v[48:49], off offset:3072
	s_add_u32 s30, s2, 0
	s_addc_u32 s31, s3, 0
	s_add_u32 s34, s30, 0x1000
	s_addc_u32 s35, s31, 0
	global_load_dwordx4 v[32:35], v172, s[34:35] offset:0
	global_load_dwordx4 v[36:39], v172, s[34:35] offset:1024
	global_load_dwordx4 v[40:43], v172, s[34:35] offset:2048
	global_load_dwordx4 v[44:47], v172, s[34:35] offset:3072
	global_load_dwordx4 v[56:59], v172, s[30:31] offset:0
	global_load_dwordx4 v[60:63], v172, s[30:31] offset:1024
	global_load_dwordx4 v[64:67], v172, s[30:31] offset:2048
	global_load_dwordx4 v[68:71], v172, s[30:31] offset:3072
	s_add_u32 s22, s38, 0
	s_addc_u32 s23, s39, 0
	global_load_dwordx4 v[104:107], v172, s[22:23] offset:0 nt
	global_load_dwordx4 v[108:111], v172, s[22:23] offset:1024 nt
	global_load_dwordx4 v[112:115], v172, s[22:23] offset:2048 nt
	global_load_dwordx4 v[116:119], v172, s[22:23] offset:3072 nt
	s_add_u32 s22, s38, 8388608
	s_addc_u32 s23, s39, 0
	global_load_dwordx4 v[132:135], v172, s[22:23] offset:0 nt
	global_load_dwordx4 v[136:139], v172, s[22:23] offset:1024 nt
	global_load_dwordx4 v[140:143], v172, s[22:23] offset:2048 nt
	global_load_dwordx4 v[144:147], v172, s[22:23] offset:3072 nt
	s_add_u32 s22, s38, 16777216
	s_addc_u32 s23, s39, 0
	global_load_dwordx4 v[120:123], v172, s[22:23] offset:0 nt
	global_load_dwordx4 v[124:127], v172, s[22:23] offset:1024 nt
	global_load_dwordx4 v[148:151], v172, s[22:23] offset:2048 nt
	global_load_dwordx4 v[152:155], v172, s[22:23] offset:3072 nt
	s_waitcnt vmcnt(12)
	v_pk_add_f32 v[32:33], v[32:33], 1.0 op_sel_hi:[1,0]
	v_pk_add_f32 v[34:35], v[34:35], 1.0 op_sel_hi:[1,0]
	v_pk_add_f32 v[36:37], v[36:37], 1.0 op_sel_hi:[1,0]
	v_pk_add_f32 v[38:39], v[38:39], 1.0 op_sel_hi:[1,0]
	v_pk_add_f32 v[40:41], v[40:41], 1.0 op_sel_hi:[1,0]
	v_pk_add_f32 v[42:43], v[42:43], 1.0 op_sel_hi:[1,0]
	v_pk_add_f32 v[44:45], v[44:45], 1.0 op_sel_hi:[1,0]
	v_pk_add_f32 v[46:47], v[46:47], 1.0 op_sel_hi:[1,0]
	v_pk_mul_f32 v[32:33], v[236:237], v[32:33]
	v_pk_mul_f32 v[34:35], v[238:239], v[34:35]
	v_pk_mul_f32 v[36:37], v[240:241], v[36:37]
	v_pk_mul_f32 v[38:39], v[242:243], v[38:39]
	v_pk_mul_f32 v[40:41], v[244:245], v[40:41]
	v_pk_mul_f32 v[42:43], v[246:247], v[42:43]
	v_pk_mul_f32 v[44:45], v[248:249], v[44:45]
	v_pk_mul_f32 v[46:47], v[250:251], v[46:47]
	s_add_u32 s30, s2, 12288
	s_addc_u32 s31, s3, 0
	s_add_u32 s34, s30, 0x1000
	s_addc_u32 s35, s31, 0
	global_load_dwordx4 v[156:159], v172, s[34:35] offset:0
	global_load_dwordx4 v[160:163], v172, s[34:35] offset:1024
	global_load_dwordx4 v[164:167], v172, s[34:35] offset:2048
	global_load_dwordx4 v[168:171], v172, s[34:35] offset:3072
	global_load_dwordx4 v[182:185], v172, s[30:31] offset:0
	global_load_dwordx4 v[186:189], v172, s[30:31] offset:1024
	global_load_dwordx4 v[190:193], v172, s[30:31] offset:2048
	global_load_dwordx4 v[194:197], v172, s[30:31] offset:3072
	s_waitcnt vmcnt(16)
	v_cvt_pk_bf16_f32 v104, v104, v105
	v_cvt_pk_bf16_f32 v105, v106, v107
	v_cvt_pk_bf16_f32 v108, v108, v109
	v_cvt_pk_bf16_f32 v109, v110, v111
	v_cvt_pk_bf16_f32 v112, v112, v113
	v_cvt_pk_bf16_f32 v113, v114, v115
	v_cvt_pk_bf16_f32 v116, v116, v117
	v_cvt_pk_bf16_f32 v117, v118, v119
	s_add_u32 s36, s8, 0
	s_addc_u32 s37, s9, 0
	global_store_dwordx2 v231, v[104:105], s[36:37] offset:0 sc1
	global_store_dwordx2 v231, v[108:109], s[36:37] offset:512 sc1
	global_store_dwordx2 v231, v[112:113], s[36:37] offset:1024 sc1
	global_store_dwordx2 v231, v[116:117], s[36:37] offset:1536 sc1
	v_lshlrev_b32_e32 v198, 16, v104
	v_and_b32_e32 v199, 0xffff0000, v104
	v_lshlrev_b32_e32 v200, 16, v105
	v_and_b32_e32 v201, 0xffff0000, v105
	v_lshlrev_b32_e32 v202, 16, v108
	v_and_b32_e32 v203, 0xffff0000, v108
	v_lshlrev_b32_e32 v204, 16, v109
	v_and_b32_e32 v205, 0xffff0000, v109
	v_lshlrev_b32_e32 v206, 16, v112
	v_and_b32_e32 v207, 0xffff0000, v112
	v_lshlrev_b32_e32 v72, 16, v113
	v_and_b32_e32 v73, 0xffff0000, v113
	v_lshlrev_b32_e32 v74, 16, v116
	v_and_b32_e32 v75, 0xffff0000, v116
	v_lshlrev_b32_e32 v78, 16, v117
	v_and_b32_e32 v79, 0xffff0000, v117
	v_mul_f32_e32 v228, v199, v199
	v_fma_f32 v228, v198, v198, v228
	v_mul_f32_e32 v229, v201, v201
	v_fma_f32 v229, v200, v200, v229
	v_add_f32_e32 v228, v228, v229
	v_mul_f32_e32 v229, v203, v203
	v_fma_f32 v229, v202, v202, v229
	v_mul_f32_e32 v227, v205, v205
	v_fma_f32 v227, v204, v204, v227
	v_add_f32_e32 v229, v229, v227
	v_add_f32_e32 v228, v228, v229
	v_mul_f32_e32 v229, v207, v207
	v_fma_f32 v229, v206, v206, v229
	v_mul_f32_e32 v227, v73, v73
	v_fma_f32 v227, v72, v72, v227
	v_add_f32_e32 v229, v229, v227
	v_add_f32_e32 v228, v228, v229
	v_mul_f32_e32 v229, v75, v75
	v_fma_f32 v229, v74, v74, v229
	v_mul_f32_e32 v227, v79, v79
	v_fma_f32 v227, v78, v78, v227
	v_add_f32_e32 v229, v229, v227
	v_add_f32_e32 v228, v228, v229
	s_nop 1
	v_add_f32_dpp v228, v228, v228 quad_perm:[1,0,3,2] row_mask:0xf bank_mask:0xf
	s_nop 1
	v_add_f32_dpp v228, v228, v228 quad_perm:[2,3,0,1] row_mask:0xf bank_mask:0xf
	s_nop 1
	v_add_f32_dpp v228, v228, v228 row_half_mirror row_mask:0xf bank_mask:0xf
	s_nop 1
	v_add_f32_dpp v228, v228, v228 row_mirror row_mask:0xf bank_mask:0xf
	s_nop 1
	v_add_f32_dpp v228, v228, v228 row_bcast:15 row_mask:0xa bank_mask:0xf
	s_nop 1
	v_add_f32_dpp v228, v228, v228 row_bcast:31 row_mask:0xc bank_mask:0xf
	s_nop 1
	v_readlane_b32 s4, v228, 63
	s_nop 1
	v_mov_b32_e32 v210, s4
	v_fmamk_f32 v210, v210, 0x3a800000, v209
; #define NORM_LOAD(V, ROW) do { const u32x2* xr_ = (const u32x2*)(X + (size_t)(ROW) * D); _Pragma("unroll") for (int j = 0; j < 4; ++j) { const u32x2 w_ = xr_[64 * j + lane]; \
;         V[j] = (f32x4){__uint_as_float(w_.x << 16), __uint_as_float(w_.x & 0xffff0000u), __uint_as_float(w_.y << 16), __uint_as_float(w_.y & 0xffff0000u)}; } } while (0)
; __device__ __forceinline__ void p_norm(const Args& a, int l, int lane, int wave, int bid, int G) {
;     ...
; #pragma unroll 1
;     for (int n = 0; n < NPB; ++n) {
;         const float* mp = mod + (size_t)n * 3072;
;         f32x4 gs[4], sh[4];
; #pragma unroll
;         for (int j = 0; j < 4; ++j) { gs[j] = *((const f32x4*)g + 64 * j + lane) * (*((const f32x4*)(mp + D) + 64 * j + lane) + 1.0f); sh[j] = *((const f32x4*)mp + 64 * j + lane); }
; #pragma unroll 1
;         for (int r0 = gw; r0 < LP; r0 += 3 * NGW) {
;             f32x4 v0[4], v1[4], v2[4];
;             const int ra = n * LP + r0, rb = ra + NGW, rc = rb + NGW;
;             const bool hb = r0 + NGW < LP, hc = r0 + 2 * NGW < LP;
;             NORM_LOAD(v0, ra); if (hb) NORM_LOAD(v1, rb); if (hc) NORM_LOAD(v2, rc);
;             NORM_FINISH(v0, ra, gs, sh); if (hb) NORM_FINISH(v1, rb, gs, sh); if (hc) NORM_FINISH(v2, rc, gs, sh);
	v_mul_f32_e32 v227, 0x4b800000, v210
	v_cmp_gt_f32_e32 vcc, s96, v210
	s_nop 1
	v_cndmask_b32_e32 v210, v210, v227, vcc
	v_rsq_f32_e32 v210, v210
	s_nop 0
	v_mul_f32_e32 v227, 0x45800000, v210
	v_cndmask_b32_e32 v210, v210, v227, vcc
	v_pk_mul_f32 v[198:199], v[210:211], v[198:199] op_sel_hi:[0,1]
	v_pk_fma_f32 v[198:199], v[32:33], v[198:199], v[56:57]
	v_pk_mul_f32 v[200:201], v[210:211], v[200:201] op_sel_hi:[0,1]
	v_pk_fma_f32 v[200:201], v[34:35], v[200:201], v[58:59]
	v_pk_mul_f32 v[202:203], v[210:211], v[202:203] op_sel_hi:[0,1]
	v_pk_fma_f32 v[202:203], v[36:37], v[202:203], v[60:61]
	v_pk_mul_f32 v[204:205], v[210:211], v[204:205] op_sel_hi:[0,1]
	v_pk_fma_f32 v[204:205], v[38:39], v[204:205], v[62:63]
	v_pk_mul_f32 v[206:207], v[210:211], v[206:207] op_sel_hi:[0,1]
	v_pk_fma_f32 v[206:207], v[40:41], v[206:207], v[64:65]
	v_pk_mul_f32 v[72:73], v[210:211], v[72:73] op_sel_hi:[0,1]
	v_pk_fma_f32 v[72:73], v[42:43], v[72:73], v[66:67]
	v_pk_mul_f32 v[74:75], v[210:211], v[74:75] op_sel_hi:[0,1]
	v_pk_fma_f32 v[74:75], v[44:45], v[74:75], v[68:69]
	v_pk_mul_f32 v[78:79], v[210:211], v[78:79] op_sel_hi:[0,1]
	v_pk_fma_f32 v[78:79], v[46:47], v[78:79], v[70:71]
	v_cvt_pk_bf16_f32 v106, v198, v199
	v_cvt_pk_bf16_f32 v107, v200, v201
	v_cvt_pk_bf16_f32 v110, v202, v203
	v_cvt_pk_bf16_f32 v111, v204, v205
	v_cvt_pk_bf16_f32 v114, v206, v207
	v_cvt_pk_bf16_f32 v115, v72, v73
	v_cvt_pk_bf16_f32 v118, v74, v75
	v_cvt_pk_bf16_f32 v119, v78, v79
	s_add_u32 s28, s10, 0
	s_addc_u32 s29, s11, 0
	global_store_dwordx2 v231, v[106:107], s[28:29] offset:0 sc1
	global_store_dwordx2 v231, v[110:111], s[28:29] offset:512 sc1
	global_store_dwordx2 v231, v[114:115], s[28:29] offset:1024 sc1
	global_store_dwordx2 v231, v[118:119], s[28:29] offset:1536 sc1
	s_add_u32 s22, s38, 25165824
	s_addc_u32 s23, s39, 0
	global_load_dwordx4 v[104:107], v172, s[22:23] offset:0 nt
	global_load_dwordx4 v[108:111], v172, s[22:23] offset:1024 nt
	global_load_dwordx4 v[112:115], v172, s[22:23] offset:2048 nt
	global_load_dwordx4 v[116:119], v172, s[22:23] offset:3072 nt
	s_waitcnt vmcnt(24)
	v_cvt_pk_bf16_f32 v132, v132, v133
	v_cvt_pk_bf16_f32 v133, v134, v135
	v_cvt_pk_bf16_f32 v136, v136, v137
	v_cvt_pk_bf16_f32 v137, v138, v139
	v_cvt_pk_bf16_f32 v140, v140, v141
	v_cvt_pk_bf16_f32 v141, v142, v143
	v_cvt_pk_bf16_f32 v144, v144, v145
	v_cvt_pk_bf16_f32 v145, v146, v147
	s_add_u32 s36, s8, 4194304
	s_addc_u32 s37, s9, 0
	global_store_dwordx2 v231, v[132:133], s[36:37] offset:0 sc1
	global_store_dwordx2 v231, v[136:137], s[36:37] offset:512 sc1
	global_store_dwordx2 v231, v[140:141], s[36:37] offset:1024 sc1
	global_store_dwordx2 v231, v[144:145], s[36:37] offset:1536 sc1
	v_lshlrev_b32_e32 v198, 16, v132
	v_and_b32_e32 v199, 0xffff0000, v132
	v_lshlrev_b32_e32 v200, 16, v133
	v_and_b32_e32 v201, 0xffff0000, v133
	v_lshlrev_b32_e32 v202, 16, v136
	v_and_b32_e32 v203, 0xffff0000, v136
	v_lshlrev_b32_e32 v204, 16, v137
	v_and_b32_e32 v205, 0xffff0000, v137
	v_lshlrev_b32_e32 v206, 16, v140
	v_and_b32_e32 v207, 0xffff0000, v140
	v_lshlrev_b32_e32 v72, 16, v141
	v_and_b32_e32 v73, 0xffff0000, v141
	v_lshlrev_b32_e32 v74, 16, v144
	v_and_b32_e32 v75, 0xffff0000, v144
	v_lshlrev_b32_e32 v78, 16, v145
	v_and_b32_e32 v79, 0xffff0000, v145
	v_mul_f32_e32 v228, v199, v199
	v_fma_f32 v228, v198, v198, v228
	v_mul_f32_e32 v229, v201, v201
	v_fma_f32 v229, v200, v200, v229
	v_add_f32_e32 v228, v228, v229
	v_mul_f32_e32 v229, v203, v203
	v_fma_f32 v229, v202, v202, v229
	v_mul_f32_e32 v227, v205, v205
	v_fma_f32 v227, v204, v204, v227
	v_add_f32_e32 v229, v229, v227
	v_add_f32_e32 v228, v228, v229
	v_mul_f32_e32 v229, v207, v207
	v_fma_f32 v229, v206, v206, v229
	v_mul_f32_e32 v227, v73, v73
	v_fma_f32 v227, v72, v72, v227
	v_add_f32_e32 v229, v229, v227
	v_add_f32_e32 v228, v228, v229
	v_mul_f32_e32 v229, v75, v75
	v_fma_f32 v229, v74, v74, v229
	v_mul_f32_e32 v227, v79, v79
	v_fma_f32 v227, v78, v78, v227
	v_add_f32_e32 v229, v229, v227
	v_add_f32_e32 v228, v228, v229
	s_nop 1
	v_add_f32_dpp v228, v228, v228 quad_perm:[1,0,3,2] row_mask:0xf bank_mask:0xf
	s_nop 1
	v_add_f32_dpp v228, v228, v228 quad_perm:[2,3,0,1] row_mask:0xf bank_mask:0xf
	s_nop 1
	v_add_f32_dpp v228, v228, v228 row_half_mirror row_mask:0xf bank_mask:0xf
	s_nop 1
	v_add_f32_dpp v228, v228, v228 row_mirror row_mask:0xf bank_mask:0xf
	s_nop 1
	v_add_f32_dpp v228, v228, v228 row_bcast:15 row_mask:0xa bank_mask:0xf
	s_nop 1
	v_add_f32_dpp v228, v228, v228 row_bcast:31 row_mask:0xc bank_mask:0xf
	s_nop 1
	v_readlane_b32 s4, v228, 63
	s_nop 1
	v_mov_b32_e32 v210, s4
	v_fmamk_f32 v210, v210, 0x3a800000, v209
	v_mul_f32_e32 v227, 0x4b800000, v210
	v_cmp_gt_f32_e32 vcc, s96, v210
	s_nop 1
	v_cndmask_b32_e32 v210, v210, v227, vcc
	v_rsq_f32_e32 v210, v210
	s_nop 0
	v_mul_f32_e32 v227, 0x45800000, v210
	v_cndmask_b32_e32 v210, v210, v227, vcc
	v_pk_mul_f32 v[198:199], v[210:211], v[198:199] op_sel_hi:[0,1]
	v_pk_fma_f32 v[198:199], v[32:33], v[198:199], v[56:57]
	v_pk_mul_f32 v[200:201], v[210:211], v[200:201] op_sel_hi:[0,1]
	v_pk_fma_f32 v[200:201], v[34:35], v[200:201], v[58:59]
	v_pk_mul_f32 v[202:203], v[210:211], v[202:203] op_sel_hi:[0,1]
	v_pk_fma_f32 v[202:203], v[36:37], v[202:203], v[60:61]
	v_pk_mul_f32 v[204:205], v[210:211], v[204:205] op_sel_hi:[0,1]
	v_pk_fma_f32 v[204:205], v[38:39], v[204:205], v[62:63]
	v_pk_mul_f32 v[206:207], v[210:211], v[206:207] op_sel_hi:[0,1]
	v_pk_fma_f32 v[206:207], v[40:41], v[206:207], v[64:65]
	v_pk_mul_f32 v[72:73], v[210:211], v[72:73] op_sel_hi:[0,1]
	v_pk_fma_f32 v[72:73], v[42:43], v[72:73], v[66:67]
	v_pk_mul_f32 v[74:75], v[210:211], v[74:75] op_sel_hi:[0,1]
	v_pk_fma_f32 v[74:75], v[44:45], v[74:75], v[68:69]
	v_pk_mul_f32 v[78:79], v[210:211], v[78:79] op_sel_hi:[0,1]
	v_pk_fma_f32 v[78:79], v[46:47], v[78:79], v[70:71]
	v_cvt_pk_bf16_f32 v134, v198, v199
	v_cvt_pk_bf16_f32 v135, v200, v201
	v_cvt_pk_bf16_f32 v138, v202, v203
	v_cvt_pk_bf16_f32 v139, v204, v205
	v_cvt_pk_bf16_f32 v142, v206, v207
	v_cvt_pk_bf16_f32 v143, v72, v73
	v_cvt_pk_bf16_f32 v146, v74, v75
	v_cvt_pk_bf16_f32 v147, v78, v79
	s_add_u32 s28, s10, 4194304
	s_addc_u32 s29, s11, 0
	global_store_dwordx2 v231, v[134:135], s[28:29] offset:0 sc1
	global_store_dwordx2 v231, v[138:139], s[28:29] offset:512 sc1
	global_store_dwordx2 v231, v[142:143], s[28:29] offset:1024 sc1
	global_store_dwordx2 v231, v[146:147], s[28:29] offset:1536 sc1
	s_add_u32 s22, s38, 33554432
	s_addc_u32 s23, s39, 0
	global_load_dwordx4 v[132:135], v172, s[22:23] offset:0 nt
	global_load_dwordx4 v[136:139], v172, s[22:23] offset:1024 nt
	global_load_dwordx4 v[140:143], v172, s[22:23] offset:2048 nt
	global_load_dwordx4 v[144:147], v172, s[22:23] offset:3072 nt
	s_waitcnt vmcnt(24)
; #define NORM_LOAD(V, ROW) do { const u32x2* xr_ = (const u32x2*)(X + (size_t)(ROW) * D); _Pragma("unroll") for (int j = 0; j < 4; ++j) { const u32x2 w_ = xr_[64 * j + lane]; \
;         V[j] = (f32x4){__uint_as_float(w_.x << 16), __uint_as_float(w_.x & 0xffff0000u), __uint_as_float(w_.y << 16), __uint_as_float(w_.y & 0xffff0000u)}; } } while (0)
; __device__ __forceinline__ void p_norm(const Args& a, int l, int lane, int wave, int bid, int G) {
;     ...
; #pragma unroll 1
;     for (int n = 0; n < NPB; ++n) {
;         const float* mp = mod + (size_t)n * 3072;
;         f32x4 gs[4], sh[4];
; #pragma unroll
;         for (int j = 0; j < 4; ++j) { gs[j] = *((const f32x4*)g + 64 * j + lane) * (*((const f32x4*)(mp + D) + 64 * j + lane) + 1.0f); sh[j] = *((const f32x4*)mp + 64 * j + lane); }
; #pragma unroll 1
;         for (int r0 = gw; r0 < LP; r0 += 3 * NGW) {
;             f32x4 v0[4], v1[4], v2[4];
;             const int ra = n * LP + r0, rb = ra + NGW, rc = rb + NGW;
;             const bool hb = r0 + NGW < LP, hc = r0 + 2 * NGW < LP;
;             NORM_LOAD(v0, ra); if (hb) NORM_LOAD(v1, rb); if (hc) NORM_LOAD(v2, rc);
;             NORM_FINISH(v0, ra, gs, sh); if (hb) NORM_FINISH(v1, rb, gs, sh); if (hc) NORM_FINISH(v2, rc, gs, sh);
	v_pk_add_f32 v[156:157], v[156:157], 1.0 op_sel_hi:[1,0]
	v_pk_add_f32 v[158:159], v[158:159], 1.0 op_sel_hi:[1,0]
	v_pk_add_f32 v[160:161], v[160:161], 1.0 op_sel_hi:[1,0]
	v_pk_add_f32 v[162:163], v[162:163], 1.0 op_sel_hi:[1,0]
	v_pk_add_f32 v[164:165], v[164:165], 1.0 op_sel_hi:[1,0]
	v_pk_add_f32 v[166:167], v[166:167], 1.0 op_sel_hi:[1,0]
	v_pk_add_f32 v[168:169], v[168:169], 1.0 op_sel_hi:[1,0]
	v_pk_add_f32 v[170:171], v[170:171], 1.0 op_sel_hi:[1,0]
	v_pk_mul_f32 v[156:157], v[236:237], v[156:157]
	v_pk_mul_f32 v[158:159], v[238:239], v[158:159]
	v_pk_mul_f32 v[160:161], v[240:241], v[160:161]
	v_pk_mul_f32 v[162:163], v[242:243], v[162:163]
	v_pk_mul_f32 v[164:165], v[244:245], v[164:165]
	v_pk_mul_f32 v[166:167], v[246:247], v[166:167]
	v_pk_mul_f32 v[168:169], v[248:249], v[168:169]
	v_pk_mul_f32 v[170:171], v[250:251], v[170:171]
	s_add_u32 s30, s2, 24576
	s_addc_u32 s31, s3, 0
	s_add_u32 s34, s30, 0x1000
	s_addc_u32 s35, s31, 0
	global_load_dwordx4 v[32:35], v172, s[34:35] offset:0
	global_load_dwordx4 v[36:39], v172, s[34:35] offset:1024
	global_load_dwordx4 v[40:43], v172, s[34:35] offset:2048
	global_load_dwordx4 v[44:47], v172, s[34:35] offset:3072
	global_load_dwordx4 v[56:59], v172, s[30:31] offset:0
	global_load_dwordx4 v[60:63], v172, s[30:31] offset:1024
	global_load_dwordx4 v[64:67], v172, s[30:31] offset:2048
	global_load_dwordx4 v[68:71], v172, s[30:31] offset:3072
	s_waitcnt vmcnt(40)
	v_cvt_pk_bf16_f32 v120, v120, v121
	v_cvt_pk_bf16_f32 v121, v122, v123
	v_cvt_pk_bf16_f32 v124, v124, v125
	v_cvt_pk_bf16_f32 v125, v126, v127
	v_cvt_pk_bf16_f32 v148, v148, v149
	v_cvt_pk_bf16_f32 v149, v150, v151
	v_cvt_pk_bf16_f32 v152, v152, v153
	v_cvt_pk_bf16_f32 v153, v154, v155
	s_add_u32 s36, s8, 8388608
	s_addc_u32 s37, s9, 0
	global_store_dwordx2 v231, v[120:121], s[36:37] offset:0 sc1
	global_store_dwordx2 v231, v[124:125], s[36:37] offset:512 sc1
	global_store_dwordx2 v231, v[148:149], s[36:37] offset:1024 sc1
	global_store_dwordx2 v231, v[152:153], s[36:37] offset:1536 sc1
	v_lshlrev_b32_e32 v198, 16, v120
	v_and_b32_e32 v199, 0xffff0000, v120
	v_lshlrev_b32_e32 v200, 16, v121
	v_and_b32_e32 v201, 0xffff0000, v121
	v_lshlrev_b32_e32 v202, 16, v124
	v_and_b32_e32 v203, 0xffff0000, v124
	v_lshlrev_b32_e32 v204, 16, v125
	v_and_b32_e32 v205, 0xffff0000, v125
	v_lshlrev_b32_e32 v206, 16, v148
	v_and_b32_e32 v207, 0xffff0000, v148
	v_lshlrev_b32_e32 v72, 16, v149
	v_and_b32_e32 v73, 0xffff0000, v149
	v_lshlrev_b32_e32 v74, 16, v152
	v_and_b32_e32 v75, 0xffff0000, v152
	v_lshlrev_b32_e32 v78, 16, v153
	v_and_b32_e32 v79, 0xffff0000, v153
	v_mul_f32_e32 v228, v199, v199
	v_fma_f32 v228, v198, v198, v228
	v_mul_f32_e32 v229, v201, v201
	v_fma_f32 v229, v200, v200, v229
	v_add_f32_e32 v228, v228, v229
	v_mul_f32_e32 v229, v203, v203
	v_fma_f32 v229, v202, v202, v229
	v_mul_f32_e32 v227, v205, v205
	v_fma_f32 v227, v204, v204, v227
	v_add_f32_e32 v229, v229, v227
	v_add_f32_e32 v228, v228, v229
	v_mul_f32_e32 v229, v207, v207
	v_fma_f32 v229, v206, v206, v229
	v_mul_f32_e32 v227, v73, v73
	v_fma_f32 v227, v72, v72, v227
	v_add_f32_e32 v229, v229, v227
	v_add_f32_e32 v228, v228, v229
	v_mul_f32_e32 v229, v75, v75
	v_fma_f32 v229, v74, v74, v229
	v_mul_f32_e32 v227, v79, v79
	v_fma_f32 v227, v78, v78, v227
	v_add_f32_e32 v229, v229, v227
	v_add_f32_e32 v228, v228, v229
	s_nop 1
	v_add_f32_dpp v228, v228, v228 quad_perm:[1,0,3,2] row_mask:0xf bank_mask:0xf
	s_nop 1
	v_add_f32_dpp v228, v228, v228 quad_perm:[2,3,0,1] row_mask:0xf bank_mask:0xf
	s_nop 1
	v_add_f32_dpp v228, v228, v228 row_half_mirror row_mask:0xf bank_mask:0xf
	s_nop 1
	v_add_f32_dpp v228, v228, v228 row_mirror row_mask:0xf bank_mask:0xf
	s_nop 1
	v_add_f32_dpp v228, v228, v228 row_bcast:15 row_mask:0xa bank_mask:0xf
	s_nop 1
	v_add_f32_dpp v228, v228, v228 row_bcast:31 row_mask:0xc bank_mask:0xf
	s_nop 1
	v_readlane_b32 s4, v228, 63
	s_nop 1
	v_mov_b32_e32 v210, s4
	v_fmamk_f32 v210, v210, 0x3a800000, v209
	v_mul_f32_e32 v227, 0x4b800000, v210
	v_cmp_gt_f32_e32 vcc, s96, v210
	s_nop 1
	v_cndmask_b32_e32 v210, v210, v227, vcc
	v_rsq_f32_e32 v210, v210
	s_nop 0
	v_mul_f32_e32 v227, 0x45800000, v210
	v_cndmask_b32_e32 v210, v210, v227, vcc
	v_pk_mul_f32 v[198:199], v[210:211], v[198:199] op_sel_hi:[0,1]
	v_pk_fma_f32 v[198:199], v[156:157], v[198:199], v[182:183]
	v_pk_mul_f32 v[200:201], v[210:211], v[200:201] op_sel_hi:[0,1]
	v_pk_fma_f32 v[200:201], v[158:159], v[200:201], v[184:185]
	v_pk_mul_f32 v[202:203], v[210:211], v[202:203] op_sel_hi:[0,1]
	v_pk_fma_f32 v[202:203], v[160:161], v[202:203], v[186:187]
	v_pk_mul_f32 v[204:205], v[210:211], v[204:205] op_sel_hi:[0,1]
	v_pk_fma_f32 v[204:205], v[162:163], v[204:205], v[188:189]
	v_pk_mul_f32 v[206:207], v[210:211], v[206:207] op_sel_hi:[0,1]
	v_pk_fma_f32 v[206:207], v[164:165], v[206:207], v[190:191]
	v_pk_mul_f32 v[72:73], v[210:211], v[72:73] op_sel_hi:[0,1]
	v_pk_fma_f32 v[72:73], v[166:167], v[72:73], v[192:193]
	v_pk_mul_f32 v[74:75], v[210:211], v[74:75] op_sel_hi:[0,1]
	v_pk_fma_f32 v[74:75], v[168:169], v[74:75], v[194:195]
	v_pk_mul_f32 v[78:79], v[210:211], v[78:79] op_sel_hi:[0,1]
	v_pk_fma_f32 v[78:79], v[170:171], v[78:79], v[196:197]
	v_cvt_pk_bf16_f32 v122, v198, v199
	v_cvt_pk_bf16_f32 v123, v200, v201
	v_cvt_pk_bf16_f32 v126, v202, v203
	v_cvt_pk_bf16_f32 v127, v204, v205
	v_cvt_pk_bf16_f32 v150, v206, v207
	v_cvt_pk_bf16_f32 v151, v72, v73
	v_cvt_pk_bf16_f32 v154, v74, v75
	v_cvt_pk_bf16_f32 v155, v78, v79
	s_add_u32 s28, s10, 8388608
	s_addc_u32 s29, s11, 0
	global_store_dwordx2 v231, v[122:123], s[28:29] offset:0 sc1
	global_store_dwordx2 v231, v[126:127], s[28:29] offset:512 sc1
	global_store_dwordx2 v231, v[150:151], s[28:29] offset:1024 sc1
	global_store_dwordx2 v231, v[154:155], s[28:29] offset:1536 sc1
	s_add_u32 s22, s38, 41943040
	s_addc_u32 s23, s39, 0
	global_load_dwordx4 v[120:123], v172, s[22:23] offset:0 nt
	global_load_dwordx4 v[124:127], v172, s[22:23] offset:1024 nt
	global_load_dwordx4 v[148:151], v172, s[22:23] offset:2048 nt
	global_load_dwordx4 v[152:155], v172, s[22:23] offset:3072 nt
	s_waitcnt vmcnt(32)
; #define NORM_LOAD(V, ROW) do { const u32x2* xr_ = (const u32x2*)(X + (size_t)(ROW) * D); _Pragma("unroll") for (int j = 0; j < 4; ++j) { const u32x2 w_ = xr_[64 * j + lane]; \
;         V[j] = (f32x4){__uint_as_float(w_.x << 16), __uint_as_float(w_.x & 0xffff0000u), __uint_as_float(w_.y << 16), __uint_as_float(w_.y & 0xffff0000u)}; } } while (0)
; __device__ __forceinline__ void p_norm(const Args& a, int l, int lane, int wave, int bid, int G) {
;     ...
; #pragma unroll 1
;     for (int n = 0; n < NPB; ++n) {
;         const float* mp = mod + (size_t)n * 3072;
;         f32x4 gs[4], sh[4];
; #pragma unroll
;         for (int j = 0; j < 4; ++j) { gs[j] = *((const f32x4*)g + 64 * j + lane) * (*((const f32x4*)(mp + D) + 64 * j + lane) + 1.0f); sh[j] = *((const f32x4*)mp + 64 * j + lane); }
; #pragma unroll 1
;         for (int r0 = gw; r0 < LP; r0 += 3 * NGW) {
;             f32x4 v0[4], v1[4], v2[4];
;             const int ra = n * LP + r0, rb = ra + NGW, rc = rb + NGW;
;             const bool hb = r0 + NGW < LP, hc = r0 + 2 * NGW < LP;
;             NORM_LOAD(v0, ra); if (hb) NORM_LOAD(v1, rb); if (hc) NORM_LOAD(v2, rc);
;             NORM_FINISH(v0, ra, gs, sh); if (hb) NORM_FINISH(v1, rb, gs, sh); if (hc) NORM_FINISH(v2, rc, gs, sh);
	v_cvt_pk_bf16_f32 v104, v104, v105
	v_cvt_pk_bf16_f32 v105, v106, v107
	v_cvt_pk_bf16_f32 v108, v108, v109
	v_cvt_pk_bf16_f32 v109, v110, v111
	v_cvt_pk_bf16_f32 v112, v112, v113
	v_cvt_pk_bf16_f32 v113, v114, v115
	v_cvt_pk_bf16_f32 v116, v116, v117
	v_cvt_pk_bf16_f32 v117, v118, v119
	s_add_u32 s36, s8, 12582912
	s_addc_u32 s37, s9, 0
	global_store_dwordx2 v231, v[104:105], s[36:37] offset:0 sc1
	global_store_dwordx2 v231, v[108:109], s[36:37] offset:512 sc1
	global_store_dwordx2 v231, v[112:113], s[36:37] offset:1024 sc1
	global_store_dwordx2 v231, v[116:117], s[36:37] offset:1536 sc1
	v_lshlrev_b32_e32 v198, 16, v104
	v_and_b32_e32 v199, 0xffff0000, v104
	v_lshlrev_b32_e32 v200, 16, v105
	v_and_b32_e32 v201, 0xffff0000, v105
	v_lshlrev_b32_e32 v202, 16, v108
	v_and_b32_e32 v203, 0xffff0000, v108
	v_lshlrev_b32_e32 v204, 16, v109
	v_and_b32_e32 v205, 0xffff0000, v109
	v_lshlrev_b32_e32 v206, 16, v112
	v_and_b32_e32 v207, 0xffff0000, v112
	v_lshlrev_b32_e32 v72, 16, v113
	v_and_b32_e32 v73, 0xffff0000, v113
	v_lshlrev_b32_e32 v74, 16, v116
	v_and_b32_e32 v75, 0xffff0000, v116
	v_lshlrev_b32_e32 v78, 16, v117
	v_and_b32_e32 v79, 0xffff0000, v117
	v_mul_f32_e32 v228, v199, v199
	v_fma_f32 v228, v198, v198, v228
	v_mul_f32_e32 v229, v201, v201
	v_fma_f32 v229, v200, v200, v229
	v_add_f32_e32 v228, v228, v229
	v_mul_f32_e32 v229, v203, v203
	v_fma_f32 v229, v202, v202, v229
	v_mul_f32_e32 v227, v205, v205
	v_fma_f32 v227, v204, v204, v227
	v_add_f32_e32 v229, v229, v227
	v_add_f32_e32 v228, v228, v229
	v_mul_f32_e32 v229, v207, v207
	v_fma_f32 v229, v206, v206, v229
	v_mul_f32_e32 v227, v73, v73
	v_fma_f32 v227, v72, v72, v227
	v_add_f32_e32 v229, v229, v227
	v_add_f32_e32 v228, v228, v229
	v_mul_f32_e32 v229, v75, v75
	v_fma_f32 v229, v74, v74, v229
	v_mul_f32_e32 v227, v79, v79
	v_fma_f32 v227, v78, v78, v227
	v_add_f32_e32 v229, v229, v227
	v_add_f32_e32 v228, v228, v229
	s_nop 1
	v_add_f32_dpp v228, v228, v228 quad_perm:[1,0,3,2] row_mask:0xf bank_mask:0xf
	s_nop 1
	v_add_f32_dpp v228, v228, v228 quad_perm:[2,3,0,1] row_mask:0xf bank_mask:0xf
	s_nop 1
	v_add_f32_dpp v228, v228, v228 row_half_mirror row_mask:0xf bank_mask:0xf
	s_nop 1
	v_add_f32_dpp v228, v228, v228 row_mirror row_mask:0xf bank_mask:0xf
	s_nop 1
	v_add_f32_dpp v228, v228, v228 row_bcast:15 row_mask:0xa bank_mask:0xf
	s_nop 1
	v_add_f32_dpp v228, v228, v228 row_bcast:31 row_mask:0xc bank_mask:0xf
	s_nop 1
	v_readlane_b32 s4, v228, 63
	s_nop 1
	v_mov_b32_e32 v210, s4
	v_fmamk_f32 v210, v210, 0x3a800000, v209
	v_mul_f32_e32 v227, 0x4b800000, v210
	v_cmp_gt_f32_e32 vcc, s96, v210
	s_nop 1
	v_cndmask_b32_e32 v210, v210, v227, vcc
	v_rsq_f32_e32 v210, v210
	s_nop 0
	v_mul_f32_e32 v227, 0x45800000, v210
	v_cndmask_b32_e32 v210, v210, v227, vcc
	v_pk_mul_f32 v[198:199], v[210:211], v[198:199] op_sel_hi:[0,1]
	v_pk_fma_f32 v[198:199], v[156:157], v[198:199], v[182:183]
	v_pk_mul_f32 v[200:201], v[210:211], v[200:201] op_sel_hi:[0,1]
	v_pk_fma_f32 v[200:201], v[158:159], v[200:201], v[184:185]
	v_pk_mul_f32 v[202:203], v[210:211], v[202:203] op_sel_hi:[0,1]
	v_pk_fma_f32 v[202:203], v[160:161], v[202:203], v[186:187]
	v_pk_mul_f32 v[204:205], v[210:211], v[204:205] op_sel_hi:[0,1]
	v_pk_fma_f32 v[204:205], v[162:163], v[204:205], v[188:189]
	v_pk_mul_f32 v[206:207], v[210:211], v[206:207] op_sel_hi:[0,1]
	v_pk_fma_f32 v[206:207], v[164:165], v[206:207], v[190:191]
	v_pk_mul_f32 v[72:73], v[210:211], v[72:73] op_sel_hi:[0,1]
	v_pk_fma_f32 v[72:73], v[166:167], v[72:73], v[192:193]
	v_pk_mul_f32 v[74:75], v[210:211], v[74:75] op_sel_hi:[0,1]
	v_pk_fma_f32 v[74:75], v[168:169], v[74:75], v[194:195]
	v_pk_mul_f32 v[78:79], v[210:211], v[78:79] op_sel_hi:[0,1]
	v_pk_fma_f32 v[78:79], v[170:171], v[78:79], v[196:197]
	v_cvt_pk_bf16_f32 v106, v198, v199
	v_cvt_pk_bf16_f32 v107, v200, v201
	v_cvt_pk_bf16_f32 v110, v202, v203
	v_cvt_pk_bf16_f32 v111, v204, v205
	v_cvt_pk_bf16_f32 v114, v206, v207
	v_cvt_pk_bf16_f32 v115, v72, v73
	v_cvt_pk_bf16_f32 v118, v74, v75
	v_cvt_pk_bf16_f32 v119, v78, v79
	s_add_u32 s28, s10, 12582912
	s_addc_u32 s29, s11, 0
	global_store_dwordx2 v231, v[106:107], s[28:29] offset:0 sc1
	global_store_dwordx2 v231, v[110:111], s[28:29] offset:512 sc1
	global_store_dwordx2 v231, v[114:115], s[28:29] offset:1024 sc1
	global_store_dwordx2 v231, v[118:119], s[28:29] offset:1536 sc1
	s_add_u32 s22, s38, 50331648
	s_addc_u32 s23, s39, 0
	global_load_dwordx4 v[104:107], v172, s[22:23] offset:0 nt
	global_load_dwordx4 v[108:111], v172, s[22:23] offset:1024 nt
	global_load_dwordx4 v[112:115], v172, s[22:23] offset:2048 nt
	global_load_dwordx4 v[116:119], v172, s[22:23] offset:3072 nt
	s_waitcnt vmcnt(24)
	v_pk_add_f32 v[32:33], v[32:33], 1.0 op_sel_hi:[1,0]
	v_pk_add_f32 v[34:35], v[34:35], 1.0 op_sel_hi:[1,0]
	v_pk_add_f32 v[36:37], v[36:37], 1.0 op_sel_hi:[1,0]
	v_pk_add_f32 v[38:39], v[38:39], 1.0 op_sel_hi:[1,0]
	v_pk_add_f32 v[40:41], v[40:41], 1.0 op_sel_hi:[1,0]
	v_pk_add_f32 v[42:43], v[42:43], 1.0 op_sel_hi:[1,0]
	v_pk_add_f32 v[44:45], v[44:45], 1.0 op_sel_hi:[1,0]
	v_pk_add_f32 v[46:47], v[46:47], 1.0 op_sel_hi:[1,0]
	v_pk_mul_f32 v[32:33], v[236:237], v[32:33]
	v_pk_mul_f32 v[34:35], v[238:239], v[34:35]
	v_pk_mul_f32 v[36:37], v[240:241], v[36:37]
	v_pk_mul_f32 v[38:39], v[242:243], v[38:39]
	v_pk_mul_f32 v[40:41], v[244:245], v[40:41]
	v_pk_mul_f32 v[42:43], v[246:247], v[42:43]
	v_pk_mul_f32 v[44:45], v[248:249], v[44:45]
	v_pk_mul_f32 v[46:47], v[250:251], v[46:47]
	s_add_u32 s30, s2, 36864
	s_addc_u32 s31, s3, 0
	s_add_u32 s34, s30, 0x1000
	s_addc_u32 s35, s31, 0
	global_load_dwordx4 v[156:159], v172, s[34:35] offset:0
	global_load_dwordx4 v[160:163], v172, s[34:35] offset:1024
	global_load_dwordx4 v[164:167], v172, s[34:35] offset:2048
	global_load_dwordx4 v[168:171], v172, s[34:35] offset:3072
	global_load_dwordx4 v[182:185], v172, s[30:31] offset:0
	global_load_dwordx4 v[186:189], v172, s[30:31] offset:1024
	global_load_dwordx4 v[190:193], v172, s[30:31] offset:2048
	global_load_dwordx4 v[194:197], v172, s[30:31] offset:3072
	s_waitcnt vmcnt(40)
; #define NORM_LOAD(V, ROW) do { const u32x2* xr_ = (const u32x2*)(X + (size_t)(ROW) * D); _Pragma("unroll") for (int j = 0; j < 4; ++j) { const u32x2 w_ = xr_[64 * j + lane]; \
;         V[j] = (f32x4){__uint_as_float(w_.x << 16), __uint_as_float(w_.x & 0xffff0000u), __uint_as_float(w_.y << 16), __uint_as_float(w_.y & 0xffff0000u)}; } } while (0)
; __device__ __forceinline__ void p_norm(const Args& a, int l, int lane, int wave, int bid, int G) {
;     ...
; #pragma unroll 1
;     for (int n = 0; n < NPB; ++n) {
;         const float* mp = mod + (size_t)n * 3072;
;         f32x4 gs[4], sh[4];
; #pragma unroll
;         for (int j = 0; j < 4; ++j) { gs[j] = *((const f32x4*)g + 64 * j + lane) * (*((const f32x4*)(mp + D) + 64 * j + lane) + 1.0f); sh[j] = *((const f32x4*)mp + 64 * j + lane); }
; #pragma unroll 1
;         for (int r0 = gw; r0 < LP; r0 += 3 * NGW) {
;             f32x4 v0[4], v1[4], v2[4];
;             const int ra = n * LP + r0, rb = ra + NGW, rc = rb + NGW;
;             const bool hb = r0 + NGW < LP, hc = r0 + 2 * NGW < LP;
;             NORM_LOAD(v0, ra); if (hb) NORM_LOAD(v1, rb); if (hc) NORM_LOAD(v2, rc);
;             NORM_FINISH(v0, ra, gs, sh); if (hb) NORM_FINISH(v1, rb, gs, sh); if (hc) NORM_FINISH(v2, rc, gs, sh);
	v_cvt_pk_bf16_f32 v132, v132, v133
	v_cvt_pk_bf16_f32 v133, v134, v135
	v_cvt_pk_bf16_f32 v136, v136, v137
	v_cvt_pk_bf16_f32 v137, v138, v139
	v_cvt_pk_bf16_f32 v140, v140, v141
	v_cvt_pk_bf16_f32 v141, v142, v143
	v_cvt_pk_bf16_f32 v144, v144, v145
	v_cvt_pk_bf16_f32 v145, v146, v147
	s_add_u32 s36, s8, 16777216
	s_addc_u32 s37, s9, 0
	global_store_dwordx2 v231, v[132:133], s[36:37] offset:0 sc1
	global_store_dwordx2 v231, v[136:137], s[36:37] offset:512 sc1
	global_store_dwordx2 v231, v[140:141], s[36:37] offset:1024 sc1
	global_store_dwordx2 v231, v[144:145], s[36:37] offset:1536 sc1
	v_lshlrev_b32_e32 v198, 16, v132
	v_and_b32_e32 v199, 0xffff0000, v132
	v_lshlrev_b32_e32 v200, 16, v133
	v_and_b32_e32 v201, 0xffff0000, v133
	v_lshlrev_b32_e32 v202, 16, v136
	v_and_b32_e32 v203, 0xffff0000, v136
	v_lshlrev_b32_e32 v204, 16, v137
	v_and_b32_e32 v205, 0xffff0000, v137
	v_lshlrev_b32_e32 v206, 16, v140
	v_and_b32_e32 v207, 0xffff0000, v140
	v_lshlrev_b32_e32 v72, 16, v141
	v_and_b32_e32 v73, 0xffff0000, v141
	v_lshlrev_b32_e32 v74, 16, v144
	v_and_b32_e32 v75, 0xffff0000, v144
	v_lshlrev_b32_e32 v78, 16, v145
	v_and_b32_e32 v79, 0xffff0000, v145
	v_mul_f32_e32 v228, v199, v199
	v_fma_f32 v228, v198, v198, v228
	v_mul_f32_e32 v229, v201, v201
	v_fma_f32 v229, v200, v200, v229
	v_add_f32_e32 v228, v228, v229
	v_mul_f32_e32 v229, v203, v203
	v_fma_f32 v229, v202, v202, v229
	v_mul_f32_e32 v227, v205, v205
	v_fma_f32 v227, v204, v204, v227
	v_add_f32_e32 v229, v229, v227
	v_add_f32_e32 v228, v228, v229
	v_mul_f32_e32 v229, v207, v207
	v_fma_f32 v229, v206, v206, v229
	v_mul_f32_e32 v227, v73, v73
	v_fma_f32 v227, v72, v72, v227
	v_add_f32_e32 v229, v229, v227
	v_add_f32_e32 v228, v228, v229
	v_mul_f32_e32 v229, v75, v75
	v_fma_f32 v229, v74, v74, v229
	v_mul_f32_e32 v227, v79, v79
	v_fma_f32 v227, v78, v78, v227
	v_add_f32_e32 v229, v229, v227
	v_add_f32_e32 v228, v228, v229
	s_nop 1
	v_add_f32_dpp v228, v228, v228 quad_perm:[1,0,3,2] row_mask:0xf bank_mask:0xf
	s_nop 1
	v_add_f32_dpp v228, v228, v228 quad_perm:[2,3,0,1] row_mask:0xf bank_mask:0xf
	s_nop 1
	v_add_f32_dpp v228, v228, v228 row_half_mirror row_mask:0xf bank_mask:0xf
	s_nop 1
	v_add_f32_dpp v228, v228, v228 row_mirror row_mask:0xf bank_mask:0xf
	s_nop 1
	v_add_f32_dpp v228, v228, v228 row_bcast:15 row_mask:0xa bank_mask:0xf
	s_nop 1
	v_add_f32_dpp v228, v228, v228 row_bcast:31 row_mask:0xc bank_mask:0xf
	s_nop 1
	v_readlane_b32 s4, v228, 63
	s_nop 1
	v_mov_b32_e32 v210, s4
	v_fmamk_f32 v210, v210, 0x3a800000, v209
	v_mul_f32_e32 v227, 0x4b800000, v210
	v_cmp_gt_f32_e32 vcc, s96, v210
	s_nop 1
	v_cndmask_b32_e32 v210, v210, v227, vcc
	v_rsq_f32_e32 v210, v210
	s_nop 0
	v_mul_f32_e32 v227, 0x45800000, v210
	v_cndmask_b32_e32 v210, v210, v227, vcc
	v_pk_mul_f32 v[198:199], v[210:211], v[198:199] op_sel_hi:[0,1]
	v_pk_fma_f32 v[198:199], v[32:33], v[198:199], v[56:57]
	v_pk_mul_f32 v[200:201], v[210:211], v[200:201] op_sel_hi:[0,1]
	v_pk_fma_f32 v[200:201], v[34:35], v[200:201], v[58:59]
	v_pk_mul_f32 v[202:203], v[210:211], v[202:203] op_sel_hi:[0,1]
	v_pk_fma_f32 v[202:203], v[36:37], v[202:203], v[60:61]
	v_pk_mul_f32 v[204:205], v[210:211], v[204:205] op_sel_hi:[0,1]
	v_pk_fma_f32 v[204:205], v[38:39], v[204:205], v[62:63]
	v_pk_mul_f32 v[206:207], v[210:211], v[206:207] op_sel_hi:[0,1]
	v_pk_fma_f32 v[206:207], v[40:41], v[206:207], v[64:65]
	v_pk_mul_f32 v[72:73], v[210:211], v[72:73] op_sel_hi:[0,1]
	v_pk_fma_f32 v[72:73], v[42:43], v[72:73], v[66:67]
	v_pk_mul_f32 v[74:75], v[210:211], v[74:75] op_sel_hi:[0,1]
	v_pk_fma_f32 v[74:75], v[44:45], v[74:75], v[68:69]
	v_pk_mul_f32 v[78:79], v[210:211], v[78:79] op_sel_hi:[0,1]
	v_pk_fma_f32 v[78:79], v[46:47], v[78:79], v[70:71]
	v_cvt_pk_bf16_f32 v134, v198, v199
	v_cvt_pk_bf16_f32 v135, v200, v201
	v_cvt_pk_bf16_f32 v138, v202, v203
	v_cvt_pk_bf16_f32 v139, v204, v205
	v_cvt_pk_bf16_f32 v142, v206, v207
	v_cvt_pk_bf16_f32 v143, v72, v73
	v_cvt_pk_bf16_f32 v146, v74, v75
	v_cvt_pk_bf16_f32 v147, v78, v79
	s_add_u32 s28, s10, 16777216
	s_addc_u32 s29, s11, 0
	global_store_dwordx2 v231, v[134:135], s[28:29] offset:0 sc1
	global_store_dwordx2 v231, v[138:139], s[28:29] offset:512 sc1
	global_store_dwordx2 v231, v[142:143], s[28:29] offset:1024 sc1
	global_store_dwordx2 v231, v[146:147], s[28:29] offset:1536 sc1
	s_add_u32 s22, s38, 58720256
	s_addc_u32 s23, s39, 0
	global_load_dwordx4 v[132:135], v172, s[22:23] offset:0 nt
	global_load_dwordx4 v[136:139], v172, s[22:23] offset:1024 nt
	global_load_dwordx4 v[140:143], v172, s[22:23] offset:2048 nt
	global_load_dwordx4 v[144:147], v172, s[22:23] offset:3072 nt
	s_waitcnt vmcnt(32)
; __device__ __forceinline__ void p0_phase(const Args& a, LAS unsigned char* lds, int tid, int lane, int wave, int bid, int G) {
;     ...
;             for (int r = 0; r < 8; ++r) { const int row = q * 64 + wave * 8 + r;
; #pragma unroll
;                 for (int j = 0; j < 4; ++j) { u32x2 o; o.x = pk_bf16(v[r][j].x, v[r][j].y); o.y = pk_bf16(v[r][j].z, v[r][j].w); *((u32x2*)(XB0 + (size_t)row * D) + 64 * j + lane) = o; } }
; __device__ __forceinline__ void p_norm(const Args& a, int l, int lane, int wave, int bid, int G) {
;     ...
; #pragma unroll 1
;     for (int n = 0; n < NPB; ++n) {
;         const float* mp = mod + (size_t)n * 3072;
;         f32x4 gs[4], sh[4];
; #pragma unroll
;         for (int j = 0; j < 4; ++j) { gs[j] = *((const f32x4*)g + 64 * j + lane) * (*((const f32x4*)(mp + D) + 64 * j + lane) + 1.0f); sh[j] = *((const f32x4*)mp + 64 * j + lane); }
	v_cvt_pk_bf16_f32 v120, v120, v121
	v_cvt_pk_bf16_f32 v121, v122, v123
	v_cvt_pk_bf16_f32 v124, v124, v125
	v_cvt_pk_bf16_f32 v125, v126, v127
	v_cvt_pk_bf16_f32 v148, v148, v149
	v_cvt_pk_bf16_f32 v149, v150, v151
	v_cvt_pk_bf16_f32 v152, v152, v153
	v_cvt_pk_bf16_f32 v153, v154, v155
	s_add_u32 s36, s8, 20971520
	s_addc_u32 s37, s9, 0
	global_store_dwordx2 v231, v[120:121], s[36:37] offset:0 sc1
	global_store_dwordx2 v231, v[124:125], s[36:37] offset:512 sc1
	global_store_dwordx2 v231, v[148:149], s[36:37] offset:1024 sc1
	global_store_dwordx2 v231, v[152:153], s[36:37] offset:1536 sc1
	v_lshlrev_b32_e32 v198, 16, v120
	v_and_b32_e32 v199, 0xffff0000, v120
	v_lshlrev_b32_e32 v200, 16, v121
	v_and_b32_e32 v201, 0xffff0000, v121
	v_lshlrev_b32_e32 v202, 16, v124
	v_and_b32_e32 v203, 0xffff0000, v124
	v_lshlrev_b32_e32 v204, 16, v125
	v_and_b32_e32 v205, 0xffff0000, v125
	v_lshlrev_b32_e32 v206, 16, v148
	v_and_b32_e32 v207, 0xffff0000, v148
	v_lshlrev_b32_e32 v72, 16, v149
	v_and_b32_e32 v73, 0xffff0000, v149
	v_lshlrev_b32_e32 v74, 16, v152
	v_and_b32_e32 v75, 0xffff0000, v152
	v_lshlrev_b32_e32 v78, 16, v153
	v_and_b32_e32 v79, 0xffff0000, v153
	v_mul_f32_e32 v228, v199, v199
	v_fma_f32 v228, v198, v198, v228
	v_mul_f32_e32 v229, v201, v201
	v_fma_f32 v229, v200, v200, v229
	v_add_f32_e32 v228, v228, v229
	v_mul_f32_e32 v229, v203, v203
	v_fma_f32 v229, v202, v202, v229
	v_mul_f32_e32 v227, v205, v205
	v_fma_f32 v227, v204, v204, v227
	v_add_f32_e32 v229, v229, v227
	v_add_f32_e32 v228, v228, v229
	v_mul_f32_e32 v229, v207, v207
	v_fma_f32 v229, v206, v206, v229
	v_mul_f32_e32 v227, v73, v73
	v_fma_f32 v227, v72, v72, v227
	v_add_f32_e32 v229, v229, v227
	v_add_f32_e32 v228, v228, v229
	v_mul_f32_e32 v229, v75, v75
	v_fma_f32 v229, v74, v74, v229
	v_mul_f32_e32 v227, v79, v79
	v_fma_f32 v227, v78, v78, v227
	v_add_f32_e32 v229, v229, v227
	v_add_f32_e32 v228, v228, v229
	s_nop 1
	v_add_f32_dpp v228, v228, v228 quad_perm:[1,0,3,2] row_mask:0xf bank_mask:0xf
	s_nop 1
	v_add_f32_dpp v228, v228, v228 quad_perm:[2,3,0,1] row_mask:0xf bank_mask:0xf
	s_nop 1
	v_add_f32_dpp v228, v228, v228 row_half_mirror row_mask:0xf bank_mask:0xf
	s_nop 1
	v_add_f32_dpp v228, v228, v228 row_mirror row_mask:0xf bank_mask:0xf
	s_nop 1
	v_add_f32_dpp v228, v228, v228 row_bcast:15 row_mask:0xa bank_mask:0xf
	s_nop 1
	v_add_f32_dpp v228, v228, v228 row_bcast:31 row_mask:0xc bank_mask:0xf
	s_nop 1
	v_readlane_b32 s4, v228, 63
	s_nop 1
	v_mov_b32_e32 v210, s4
	v_fmamk_f32 v210, v210, 0x3a800000, v209
	v_mul_f32_e32 v227, 0x4b800000, v210
	v_cmp_gt_f32_e32 vcc, s96, v210
	s_nop 1
	v_cndmask_b32_e32 v210, v210, v227, vcc
	v_rsq_f32_e32 v210, v210
	s_nop 0
	v_mul_f32_e32 v227, 0x45800000, v210
	v_cndmask_b32_e32 v210, v210, v227, vcc
	v_pk_mul_f32 v[198:199], v[210:211], v[198:199] op_sel_hi:[0,1]
	v_pk_fma_f32 v[198:199], v[32:33], v[198:199], v[56:57]
	v_pk_mul_f32 v[200:201], v[210:211], v[200:201] op_sel_hi:[0,1]
	v_pk_fma_f32 v[200:201], v[34:35], v[200:201], v[58:59]
	v_pk_mul_f32 v[202:203], v[210:211], v[202:203] op_sel_hi:[0,1]
	v_pk_fma_f32 v[202:203], v[36:37], v[202:203], v[60:61]
	v_pk_mul_f32 v[204:205], v[210:211], v[204:205] op_sel_hi:[0,1]
	v_pk_fma_f32 v[204:205], v[38:39], v[204:205], v[62:63]
	v_pk_mul_f32 v[206:207], v[210:211], v[206:207] op_sel_hi:[0,1]
	v_pk_fma_f32 v[206:207], v[40:41], v[206:207], v[64:65]
	v_pk_mul_f32 v[72:73], v[210:211], v[72:73] op_sel_hi:[0,1]
	v_pk_fma_f32 v[72:73], v[42:43], v[72:73], v[66:67]
	v_pk_mul_f32 v[74:75], v[210:211], v[74:75] op_sel_hi:[0,1]
	v_pk_fma_f32 v[74:75], v[44:45], v[74:75], v[68:69]
	v_pk_mul_f32 v[78:79], v[210:211], v[78:79] op_sel_hi:[0,1]
	v_pk_fma_f32 v[78:79], v[46:47], v[78:79], v[70:71]
	v_cvt_pk_bf16_f32 v122, v198, v199
	v_cvt_pk_bf16_f32 v123, v200, v201
	v_cvt_pk_bf16_f32 v126, v202, v203
	v_cvt_pk_bf16_f32 v127, v204, v205
	v_cvt_pk_bf16_f32 v150, v206, v207
	v_cvt_pk_bf16_f32 v151, v72, v73
	v_cvt_pk_bf16_f32 v154, v74, v75
	v_cvt_pk_bf16_f32 v155, v78, v79
	s_add_u32 s28, s10, 20971520
	s_addc_u32 s29, s11, 0
	global_store_dwordx2 v231, v[122:123], s[28:29] offset:0 sc1
	global_store_dwordx2 v231, v[126:127], s[28:29] offset:512 sc1
	global_store_dwordx2 v231, v[150:151], s[28:29] offset:1024 sc1
	global_store_dwordx2 v231, v[154:155], s[28:29] offset:1536 sc1
	s_waitcnt vmcnt(20)
	v_pk_add_f32 v[156:157], v[156:157], 1.0 op_sel_hi:[1,0]
	v_pk_add_f32 v[158:159], v[158:159], 1.0 op_sel_hi:[1,0]
	v_pk_add_f32 v[160:161], v[160:161], 1.0 op_sel_hi:[1,0]
	v_pk_add_f32 v[162:163], v[162:163], 1.0 op_sel_hi:[1,0]
	v_pk_add_f32 v[164:165], v[164:165], 1.0 op_sel_hi:[1,0]
	v_pk_add_f32 v[166:167], v[166:167], 1.0 op_sel_hi:[1,0]
	v_pk_add_f32 v[168:169], v[168:169], 1.0 op_sel_hi:[1,0]
	v_pk_add_f32 v[170:171], v[170:171], 1.0 op_sel_hi:[1,0]
	v_pk_mul_f32 v[156:157], v[236:237], v[156:157]
	v_pk_mul_f32 v[158:159], v[238:239], v[158:159]
	v_pk_mul_f32 v[160:161], v[240:241], v[160:161]
	v_pk_mul_f32 v[162:163], v[242:243], v[162:163]
	v_pk_mul_f32 v[164:165], v[244:245], v[164:165]
	v_pk_mul_f32 v[166:167], v[246:247], v[166:167]
	v_pk_mul_f32 v[168:169], v[248:249], v[168:169]
	v_pk_mul_f32 v[170:171], v[250:251], v[170:171]
	s_waitcnt vmcnt(28)
; __device__ __forceinline__ void p0_phase(const Args& a, LAS unsigned char* lds, int tid, int lane, int wave, int bid, int G) {
;     ...
;             for (int r = 0; r < 8; ++r) { const int row = q * 64 + wave * 8 + r;
; #pragma unroll
;                 for (int j = 0; j < 4; ++j) { u32x2 o; o.x = pk_bf16(v[r][j].x, v[r][j].y); o.y = pk_bf16(v[r][j].z, v[r][j].w); *((u32x2*)(XB0 + (size_t)row * D) + 64 * j + lane) = o; } }
	v_cvt_pk_bf16_f32 v104, v104, v105
	v_cvt_pk_bf16_f32 v105, v106, v107
	v_cvt_pk_bf16_f32 v108, v108, v109
	v_cvt_pk_bf16_f32 v109, v110, v111
	v_cvt_pk_bf16_f32 v112, v112, v113
	v_cvt_pk_bf16_f32 v113, v114, v115
	v_cvt_pk_bf16_f32 v116, v116, v117
	v_cvt_pk_bf16_f32 v117, v118, v119
	s_add_u32 s36, s8, 25165824
	s_addc_u32 s37, s9, 0
	global_store_dwordx2 v231, v[104:105], s[36:37] offset:0 sc1
	global_store_dwordx2 v231, v[108:109], s[36:37] offset:512 sc1
	global_store_dwordx2 v231, v[112:113], s[36:37] offset:1024 sc1
	global_store_dwordx2 v231, v[116:117], s[36:37] offset:1536 sc1
	v_lshlrev_b32_e32 v198, 16, v104
	v_and_b32_e32 v199, 0xffff0000, v104
	v_lshlrev_b32_e32 v200, 16, v105
	v_and_b32_e32 v201, 0xffff0000, v105
	v_lshlrev_b32_e32 v202, 16, v108
	v_and_b32_e32 v203, 0xffff0000, v108
	v_lshlrev_b32_e32 v204, 16, v109
	v_and_b32_e32 v205, 0xffff0000, v109
	v_lshlrev_b32_e32 v206, 16, v112
	v_and_b32_e32 v207, 0xffff0000, v112
	v_lshlrev_b32_e32 v72, 16, v113
	v_and_b32_e32 v73, 0xffff0000, v113
	v_lshlrev_b32_e32 v74, 16, v116
	v_and_b32_e32 v75, 0xffff0000, v116
	v_lshlrev_b32_e32 v78, 16, v117
	v_and_b32_e32 v79, 0xffff0000, v117
	v_mul_f32_e32 v228, v199, v199
	v_fma_f32 v228, v198, v198, v228
	v_mul_f32_e32 v229, v201, v201
	v_fma_f32 v229, v200, v200, v229
	v_add_f32_e32 v228, v228, v229
	v_mul_f32_e32 v229, v203, v203
	v_fma_f32 v229, v202, v202, v229
	v_mul_f32_e32 v227, v205, v205
	v_fma_f32 v227, v204, v204, v227
	v_add_f32_e32 v229, v229, v227
	v_add_f32_e32 v228, v228, v229
	v_mul_f32_e32 v229, v207, v207
	v_fma_f32 v229, v206, v206, v229
	v_mul_f32_e32 v227, v73, v73
	v_fma_f32 v227, v72, v72, v227
	v_add_f32_e32 v229, v229, v227
	v_add_f32_e32 v228, v228, v229
	v_mul_f32_e32 v229, v75, v75
	v_fma_f32 v229, v74, v74, v229
	v_mul_f32_e32 v227, v79, v79
	v_fma_f32 v227, v78, v78, v227
	v_add_f32_e32 v229, v229, v227
	v_add_f32_e32 v228, v228, v229
	s_nop 1
	v_add_f32_dpp v228, v228, v228 quad_perm:[1,0,3,2] row_mask:0xf bank_mask:0xf
	s_nop 1
	v_add_f32_dpp v228, v228, v228 quad_perm:[2,3,0,1] row_mask:0xf bank_mask:0xf
	s_nop 1
	v_add_f32_dpp v228, v228, v228 row_half_mirror row_mask:0xf bank_mask:0xf
	s_nop 1
	v_add_f32_dpp v228, v228, v228 row_mirror row_mask:0xf bank_mask:0xf
	s_nop 1
	v_add_f32_dpp v228, v228, v228 row_bcast:15 row_mask:0xa bank_mask:0xf
	s_nop 1
	v_add_f32_dpp v228, v228, v228 row_bcast:31 row_mask:0xc bank_mask:0xf
	s_nop 1
	v_readlane_b32 s4, v228, 63
	s_nop 1
	v_mov_b32_e32 v210, s4
	v_fmamk_f32 v210, v210, 0x3a800000, v209
	v_mul_f32_e32 v227, 0x4b800000, v210
	v_cmp_gt_f32_e32 vcc, s96, v210
	s_nop 1
	v_cndmask_b32_e32 v210, v210, v227, vcc
	v_rsq_f32_e32 v210, v210
	s_nop 0
	v_mul_f32_e32 v227, 0x45800000, v210
	v_cndmask_b32_e32 v210, v210, v227, vcc
	v_pk_mul_f32 v[198:199], v[210:211], v[198:199] op_sel_hi:[0,1]
	v_pk_fma_f32 v[198:199], v[156:157], v[198:199], v[182:183]
	v_pk_mul_f32 v[200:201], v[210:211], v[200:201] op_sel_hi:[0,1]
	v_pk_fma_f32 v[200:201], v[158:159], v[200:201], v[184:185]
	v_pk_mul_f32 v[202:203], v[210:211], v[202:203] op_sel_hi:[0,1]
	v_pk_fma_f32 v[202:203], v[160:161], v[202:203], v[186:187]
	v_pk_mul_f32 v[204:205], v[210:211], v[204:205] op_sel_hi:[0,1]
	v_pk_fma_f32 v[204:205], v[162:163], v[204:205], v[188:189]
	v_pk_mul_f32 v[206:207], v[210:211], v[206:207] op_sel_hi:[0,1]
	v_pk_fma_f32 v[206:207], v[164:165], v[206:207], v[190:191]
	v_pk_mul_f32 v[72:73], v[210:211], v[72:73] op_sel_hi:[0,1]
	v_pk_fma_f32 v[72:73], v[166:167], v[72:73], v[192:193]
	v_pk_mul_f32 v[74:75], v[210:211], v[74:75] op_sel_hi:[0,1]
	v_pk_fma_f32 v[74:75], v[168:169], v[74:75], v[194:195]
	v_pk_mul_f32 v[78:79], v[210:211], v[78:79] op_sel_hi:[0,1]
	v_pk_fma_f32 v[78:79], v[170:171], v[78:79], v[196:197]
	v_cvt_pk_bf16_f32 v106, v198, v199
	v_cvt_pk_bf16_f32 v107, v200, v201
	v_cvt_pk_bf16_f32 v110, v202, v203
	v_cvt_pk_bf16_f32 v111, v204, v205
	v_cvt_pk_bf16_f32 v114, v206, v207
	v_cvt_pk_bf16_f32 v115, v72, v73
	v_cvt_pk_bf16_f32 v118, v74, v75
	v_cvt_pk_bf16_f32 v119, v78, v79
	s_add_u32 s28, s10, 25165824
	s_addc_u32 s29, s11, 0
	global_store_dwordx2 v231, v[106:107], s[28:29] offset:0 sc1
	global_store_dwordx2 v231, v[110:111], s[28:29] offset:512 sc1
	global_store_dwordx2 v231, v[114:115], s[28:29] offset:1024 sc1
	global_store_dwordx2 v231, v[118:119], s[28:29] offset:1536 sc1
	s_waitcnt vmcnt(16)
; __device__ __forceinline__ void p0_phase(const Args& a, LAS unsigned char* lds, int tid, int lane, int wave, int bid, int G) {
;     ...
;             for (int r = 0; r < 8; ++r) { const int row = q * 64 + wave * 8 + r;
; #pragma unroll
;                 for (int j = 0; j < 4; ++j) { u32x2 o; o.x = pk_bf16(v[r][j].x, v[r][j].y); o.y = pk_bf16(v[r][j].z, v[r][j].w); *((u32x2*)(XB0 + (size_t)row * D) + 64 * j + lane) = o; } }
	v_cvt_pk_bf16_f32 v132, v132, v133
	v_cvt_pk_bf16_f32 v133, v134, v135
	v_cvt_pk_bf16_f32 v136, v136, v137
	v_cvt_pk_bf16_f32 v137, v138, v139
	v_cvt_pk_bf16_f32 v140, v140, v141
	v_cvt_pk_bf16_f32 v141, v142, v143
	v_cvt_pk_bf16_f32 v144, v144, v145
	v_cvt_pk_bf16_f32 v145, v146, v147
	s_add_u32 s36, s8, 29360128
	s_addc_u32 s37, s9, 0
	global_store_dwordx2 v231, v[132:133], s[36:37] offset:0 sc1
	global_store_dwordx2 v231, v[136:137], s[36:37] offset:512 sc1
	global_store_dwordx2 v231, v[140:141], s[36:37] offset:1024 sc1
	global_store_dwordx2 v231, v[144:145], s[36:37] offset:1536 sc1
	v_lshlrev_b32_e32 v198, 16, v132
	v_and_b32_e32 v199, 0xffff0000, v132
	v_lshlrev_b32_e32 v200, 16, v133
	v_and_b32_e32 v201, 0xffff0000, v133
	v_lshlrev_b32_e32 v202, 16, v136
	v_and_b32_e32 v203, 0xffff0000, v136
	v_lshlrev_b32_e32 v204, 16, v137
	v_and_b32_e32 v205, 0xffff0000, v137
	v_lshlrev_b32_e32 v206, 16, v140
	v_and_b32_e32 v207, 0xffff0000, v140
	v_lshlrev_b32_e32 v72, 16, v141
	v_and_b32_e32 v73, 0xffff0000, v141
	v_lshlrev_b32_e32 v74, 16, v144
	v_and_b32_e32 v75, 0xffff0000, v144
	v_lshlrev_b32_e32 v78, 16, v145
	v_and_b32_e32 v79, 0xffff0000, v145
	v_mul_f32_e32 v228, v199, v199
	v_fma_f32 v228, v198, v198, v228
	v_mul_f32_e32 v229, v201, v201
	v_fma_f32 v229, v200, v200, v229
	v_add_f32_e32 v228, v228, v229
	v_mul_f32_e32 v229, v203, v203
	v_fma_f32 v229, v202, v202, v229
	v_mul_f32_e32 v227, v205, v205
	v_fma_f32 v227, v204, v204, v227
	v_add_f32_e32 v229, v229, v227
	v_add_f32_e32 v228, v228, v229
	v_mul_f32_e32 v229, v207, v207
	v_fma_f32 v229, v206, v206, v229
	v_mul_f32_e32 v227, v73, v73
	v_fma_f32 v227, v72, v72, v227
	v_add_f32_e32 v229, v229, v227
	v_add_f32_e32 v228, v228, v229
	v_mul_f32_e32 v229, v75, v75
	v_fma_f32 v229, v74, v74, v229
	v_mul_f32_e32 v227, v79, v79
	v_fma_f32 v227, v78, v78, v227
	v_add_f32_e32 v229, v229, v227
	v_add_f32_e32 v228, v228, v229
	s_nop 1
	v_add_f32_dpp v228, v228, v228 quad_perm:[1,0,3,2] row_mask:0xf bank_mask:0xf
	s_nop 1
	v_add_f32_dpp v228, v228, v228 quad_perm:[2,3,0,1] row_mask:0xf bank_mask:0xf
	s_nop 1
	v_add_f32_dpp v228, v228, v228 row_half_mirror row_mask:0xf bank_mask:0xf
	s_nop 1
	v_add_f32_dpp v228, v228, v228 row_mirror row_mask:0xf bank_mask:0xf
	s_nop 1
	v_add_f32_dpp v228, v228, v228 row_bcast:15 row_mask:0xa bank_mask:0xf
	s_nop 1
	v_add_f32_dpp v228, v228, v228 row_bcast:31 row_mask:0xc bank_mask:0xf
	s_nop 1
	v_readlane_b32 s4, v228, 63
	s_nop 1
	v_mov_b32_e32 v210, s4
	v_fmamk_f32 v210, v210, 0x3a800000, v209
	v_mul_f32_e32 v227, 0x4b800000, v210
	v_cmp_gt_f32_e32 vcc, s96, v210
	s_nop 1
	v_cndmask_b32_e32 v210, v210, v227, vcc
	v_rsq_f32_e32 v210, v210
	s_nop 0
	v_mul_f32_e32 v227, 0x45800000, v210
	v_cndmask_b32_e32 v210, v210, v227, vcc
	v_pk_mul_f32 v[198:199], v[210:211], v[198:199] op_sel_hi:[0,1]
	v_pk_fma_f32 v[198:199], v[156:157], v[198:199], v[182:183]
	v_pk_mul_f32 v[200:201], v[210:211], v[200:201] op_sel_hi:[0,1]
	v_pk_fma_f32 v[200:201], v[158:159], v[200:201], v[184:185]
	v_pk_mul_f32 v[202:203], v[210:211], v[202:203] op_sel_hi:[0,1]
	v_pk_fma_f32 v[202:203], v[160:161], v[202:203], v[186:187]
	v_pk_mul_f32 v[204:205], v[210:211], v[204:205] op_sel_hi:[0,1]
	v_pk_fma_f32 v[204:205], v[162:163], v[204:205], v[188:189]
	v_pk_mul_f32 v[206:207], v[210:211], v[206:207] op_sel_hi:[0,1]
	v_pk_fma_f32 v[206:207], v[164:165], v[206:207], v[190:191]
	v_pk_mul_f32 v[72:73], v[210:211], v[72:73] op_sel_hi:[0,1]
	v_pk_fma_f32 v[72:73], v[166:167], v[72:73], v[192:193]
	v_pk_mul_f32 v[74:75], v[210:211], v[74:75] op_sel_hi:[0,1]
	v_pk_fma_f32 v[74:75], v[168:169], v[74:75], v[194:195]
	v_pk_mul_f32 v[78:79], v[210:211], v[78:79] op_sel_hi:[0,1]
	v_pk_fma_f32 v[78:79], v[170:171], v[78:79], v[196:197]
	v_cvt_pk_bf16_f32 v134, v198, v199
	v_cvt_pk_bf16_f32 v135, v200, v201
	v_cvt_pk_bf16_f32 v138, v202, v203
	v_cvt_pk_bf16_f32 v139, v204, v205
	v_cvt_pk_bf16_f32 v142, v206, v207
	v_cvt_pk_bf16_f32 v143, v72, v73
	v_cvt_pk_bf16_f32 v146, v74, v75
	v_cvt_pk_bf16_f32 v147, v78, v79
	s_add_u32 s28, s10, 29360128
	s_addc_u32 s29, s11, 0
	global_store_dwordx2 v231, v[134:135], s[28:29] offset:0 sc1
	global_store_dwordx2 v231, v[138:139], s[28:29] offset:512 sc1
	global_store_dwordx2 v231, v[142:143], s[28:29] offset:1024 sc1
	global_store_dwordx2 v231, v[146:147], s[28:29] offset:1536 sc1
	v_lshlrev_b32_e32 v172, 4, v50
	s_branch .LBB0_207
	s_branch .LBB0_193
